# pipelined serialized load chains: ssd dt-GEMV XB loads, gmlp bs loads, attention 2-deep K/V staging, SwiGLU epilogue rs loads
# speedup vs baseline: 1.0238x; 1.0238x over previous
.LBB0_327:
	s_mov_b32 s70, 0xfffd0000
	s_mov_b32 s71, -1
	s_mov_b32 s72, 0xfffe0000
	s_mov_b32 s73, -1
	s_mov_b32 s74, 0xffff0000
	s_mov_b32 s75, -1
	v_lshl_add_u64 v[188:189], v[78:79], 0, s[70:71]
	v_lshl_add_u64 v[190:191], v[78:79], 0, s[72:73]
	v_lshl_add_u64 v[192:193], v[78:79], 0, s[74:75]
	v_mov_b64_e32 v[194:195], v[78:79]
	global_load_dwordx4 v[114:117], v[188:189], off offset:-768
	global_load_dwordx4 v[118:121], v[190:191], off offset:-768
	global_load_dwordx4 v[122:125], v[192:193], off offset:-768
	global_load_dwordx4 v[126:129], v[194:195], off offset:-768
	global_load_dwordx4 v[130:133], v[188:189], off offset:-512
	global_load_dwordx4 v[134:137], v[190:191], off offset:-512
	global_load_dwordx4 v[138:141], v[192:193], off offset:-512
	global_load_dwordx4 v[142:145], v[194:195], off offset:-512
	global_load_dwordx4 v[146:149], v[188:189], off offset:-256
	global_load_dwordx4 v[150:153], v[190:191], off offset:-256
	global_load_dwordx4 v[154:157], v[192:193], off offset:-256
	global_load_dwordx4 v[158:161], v[194:195], off offset:-256
	global_load_dwordx4 v[162:165], v[188:189], off
	global_load_dwordx4 v[176:179], v[190:191], off
	global_load_dwordx4 v[180:183], v[192:193], off
	global_load_dwordx4 v[184:187], v[194:195], off
	s_mov_b32 s5, 0xfffd0000
	v_add_co_u32_e32 v88, vcc, s5, v78
	v_add_u32_e32 v2, s4, v104
	s_nop 0
	v_addc_co_u32_e32 v89, vcc, -1, v79, vcc
	v_add_u32_e32 v60, 0x11000, v2
	ds_read_b128 v[72:75], v60
	v_add_u32_e32 v60, 0x11010, v2
	ds_read_b128 v[68:71], v60
	v_add_u32_e32 v60, 0x11020, v2
	ds_read_b128 v[64:67], v60
	v_add_u32_e32 v60, 0x11030, v2
	ds_read_b128 v[60:63], v60
	s_mov_b32 s5, 0xfffe0000
	s_addk_i32 s4, 0x1000
	s_mov_b64 s[6:7], 0x400
	s_cmpk_eq_i32 s4, 0x2000
	s_waitcnt vmcnt(15)
	v_mov_b64_e32 v[90:91], v[114:115]
	v_mov_b64_e32 v[92:93], v[116:117]
	global_load_dwordx4 v[114:117], v[188:189], off offset:256
	v_lshlrev_b32_e32 v94, 16, v90
	v_and_b32_e32 v90, 0xffff0000, v90
	v_lshlrev_b32_e32 v96, 16, v91
	v_and_b32_e32 v98, 0xffff0000, v91
	s_waitcnt lgkmcnt(3)
	v_pk_mul_f32 v[90:91], v[74:75], v[90:91] op_sel_hi:[1,0]
	v_lshlrev_b32_e32 v100, 16, v92
	v_pk_fma_f32 v[90:91], v[72:73], v[94:95], v[90:91] op_sel_hi:[1,0,1]
	v_and_b32_e32 v92, 0xffff0000, v92
	v_pk_add_f32 v[84:85], v[84:85], v[90:91]
	s_waitcnt lgkmcnt(2)
	v_pk_mul_f32 v[90:91], v[70:71], v[98:99] op_sel_hi:[1,0]
	v_and_b32_e32 v108, 0xffff0000, v93
	v_pk_fma_f32 v[90:91], v[68:69], v[96:97], v[90:91] op_sel_hi:[1,0,1]
	v_lshlrev_b32_e32 v106, 16, v93
	v_pk_add_f32 v[84:85], v[90:91], v[84:85]
	s_waitcnt lgkmcnt(1)
	v_pk_mul_f32 v[90:91], v[66:67], v[92:93] op_sel_hi:[1,0]
	s_nop 0
	v_pk_fma_f32 v[90:91], v[64:65], v[100:101], v[90:91] op_sel_hi:[1,0,1]
	s_nop 0
	v_pk_add_f32 v[84:85], v[90:91], v[84:85]
	s_waitcnt lgkmcnt(0)
	v_pk_mul_f32 v[90:91], v[62:63], v[108:109] op_sel_hi:[1,0]
	s_nop 0
	v_pk_fma_f32 v[90:91], v[60:61], v[106:107], v[90:91] op_sel_hi:[1,0,1]
	s_nop 0
	v_pk_add_f32 v[84:85], v[90:91], v[84:85]
	v_add_co_u32_e32 v90, vcc, s5, v78
	s_nop 1
	v_addc_co_u32_e32 v91, vcc, -1, v79, vcc
	s_waitcnt vmcnt(15)
	v_mov_b64_e32 v[92:93], v[118:119]
	v_mov_b64_e32 v[94:95], v[120:121]
	global_load_dwordx4 v[118:121], v[190:191], off offset:256
	v_lshlrev_b32_e32 v96, 16, v92
	v_and_b32_e32 v92, 0xffff0000, v92
	v_lshlrev_b32_e32 v98, 16, v93
	v_and_b32_e32 v100, 0xffff0000, v93
	v_pk_mul_f32 v[92:93], v[74:75], v[92:93] op_sel_hi:[1,0]
	v_lshlrev_b32_e32 v106, 16, v94
	v_pk_fma_f32 v[92:93], v[72:73], v[96:97], v[92:93] op_sel_hi:[1,0,1]
	v_and_b32_e32 v94, 0xffff0000, v94
	v_pk_add_f32 v[82:83], v[82:83], v[92:93]
	v_pk_mul_f32 v[92:93], v[70:71], v[100:101] op_sel_hi:[1,0]
	v_and_b32_e32 v110, 0xffff0000, v95
	v_pk_fma_f32 v[92:93], v[68:69], v[98:99], v[92:93] op_sel_hi:[1,0,1]
	v_lshlrev_b32_e32 v108, 16, v95
	v_pk_add_f32 v[82:83], v[92:93], v[82:83]
	v_pk_mul_f32 v[92:93], v[66:67], v[94:95] op_sel_hi:[1,0]
	s_nop 0
	v_pk_fma_f32 v[92:93], v[64:65], v[106:107], v[92:93] op_sel_hi:[1,0,1]
	s_nop 0
	v_pk_add_f32 v[82:83], v[92:93], v[82:83]
	v_pk_mul_f32 v[92:93], v[62:63], v[110:111] op_sel_hi:[1,0]
	s_nop 0
	v_pk_fma_f32 v[92:93], v[60:61], v[108:109], v[92:93] op_sel_hi:[1,0,1]
	s_nop 0
	v_pk_add_f32 v[94:95], v[92:93], v[82:83]
	v_add_co_u32_e32 v92, vcc, s33, v78
	s_nop 1
	v_addc_co_u32_e32 v93, vcc, -1, v79, vcc
	s_waitcnt vmcnt(15)
	v_mov_b64_e32 v[106:107], v[122:123]
	v_mov_b64_e32 v[108:109], v[124:125]
	global_load_dwordx4 v[122:125], v[192:193], off offset:256
	v_and_b32_e32 v96, 0xffff0000, v106
	v_lshlrev_b32_e32 v82, 16, v106
	v_pk_mul_f32 v[96:97], v[74:75], v[96:97] op_sel_hi:[1,0]
	v_and_b32_e32 v100, 0xffff0000, v107
	v_pk_fma_f32 v[82:83], v[72:73], v[82:83], v[96:97] op_sel_hi:[1,0,1]
	v_lshlrev_b32_e32 v98, 16, v107
	v_pk_add_f32 v[80:81], v[80:81], v[82:83]
	v_pk_mul_f32 v[82:83], v[70:71], v[100:101] op_sel_hi:[1,0]
	v_lshlrev_b32_e32 v106, 16, v108
	v_and_b32_e32 v108, 0xffff0000, v108
	v_pk_fma_f32 v[82:83], v[68:69], v[98:99], v[82:83] op_sel_hi:[1,0,1]
	v_and_b32_e32 v112, 0xffff0000, v109
	v_pk_add_f32 v[80:81], v[82:83], v[80:81]
	v_pk_mul_f32 v[82:83], v[66:67], v[108:109] op_sel_hi:[1,0]
	v_lshlrev_b32_e32 v110, 16, v109
	v_pk_fma_f32 v[82:83], v[64:65], v[106:107], v[82:83] op_sel_hi:[1,0,1]
	s_nop 0
	v_pk_add_f32 v[80:81], v[82:83], v[80:81]
	v_pk_mul_f32 v[82:83], v[62:63], v[112:113] op_sel_hi:[1,0]
	s_nop 0
	v_pk_fma_f32 v[82:83], v[60:61], v[110:111], v[82:83] op_sel_hi:[1,0,1]
	s_nop 0
	v_pk_add_f32 v[96:97], v[82:83], v[80:81]
	s_waitcnt vmcnt(15)
	v_mov_b64_e32 v[80:81], v[126:127]
	v_mov_b64_e32 v[82:83], v[128:129]
	global_load_dwordx4 v[126:129], v[194:195], off offset:256
	v_lshlrev_b32_e32 v108, 16, v82
	v_and_b32_e32 v82, 0xffff0000, v82
	v_and_b32_e32 v106, 0xffff0000, v81
	v_pk_mul_f32 v[66:67], v[66:67], v[82:83] op_sel_hi:[1,0]
	v_pk_mul_f32 v[70:71], v[70:71], v[106:107] op_sel_hi:[1,0]
	v_pk_fma_f32 v[64:65], v[64:65], v[108:109], v[66:67] op_sel_hi:[1,0,1]
	v_lshlrev_b32_e32 v98, 16, v80
	v_and_b32_e32 v80, 0xffff0000, v80
	v_pk_mul_f32 v[74:75], v[74:75], v[80:81] op_sel_hi:[1,0]
	v_lshlrev_b32_e32 v100, 16, v81
	v_pk_fma_f32 v[72:73], v[72:73], v[98:99], v[74:75] op_sel_hi:[1,0,1]
	v_and_b32_e32 v112, 0xffff0000, v83
	v_pk_add_f32 v[72:73], v[86:87], v[72:73]
	v_pk_fma_f32 v[68:69], v[68:69], v[100:101], v[70:71] op_sel_hi:[1,0,1]
	v_lshlrev_b32_e32 v110, 16, v83
	v_pk_add_f32 v[68:69], v[68:69], v[72:73]
	v_pk_mul_f32 v[62:63], v[62:63], v[112:113] op_sel_hi:[1,0]
	v_pk_add_f32 v[64:65], v[64:65], v[68:69]
	v_pk_fma_f32 v[60:61], v[60:61], v[110:111], v[62:63] op_sel_hi:[1,0,1]
	s_waitcnt vmcnt(15)
	v_mov_b64_e32 v[106:107], v[130:131]
	v_mov_b64_e32 v[108:109], v[132:133]
	global_load_dwordx4 v[130:133], v[188:189], off offset:512
	v_and_b32_e32 v86, 0xffff0000, v106
	v_pk_add_f32 v[80:81], v[60:61], v[64:65]
	v_add_u32_e32 v60, 0x11400, v2
	ds_read_b128 v[72:75], v60
	v_add_u32_e32 v60, 0x11410, v2
	ds_read_b128 v[68:71], v60
	v_add_u32_e32 v60, 0x11420, v2
	ds_read_b128 v[64:67], v60
	v_add_u32_e32 v60, 0x11430, v2
	v_lshlrev_b32_e32 v82, 16, v106
	s_waitcnt lgkmcnt(2)
	v_pk_mul_f32 v[86:87], v[74:75], v[86:87] op_sel_hi:[1,0]
	ds_read_b128 v[60:63], v60
	v_and_b32_e32 v100, 0xffff0000, v107
	v_pk_fma_f32 v[82:83], v[72:73], v[82:83], v[86:87] op_sel_hi:[1,0,1]
	v_lshlrev_b32_e32 v98, 16, v107
	v_pk_add_f32 v[82:83], v[84:85], v[82:83]
	s_waitcnt lgkmcnt(2)
	v_pk_mul_f32 v[84:85], v[70:71], v[100:101] op_sel_hi:[1,0]
	v_lshlrev_b32_e32 v106, 16, v108
	v_and_b32_e32 v108, 0xffff0000, v108
	v_pk_fma_f32 v[84:85], v[68:69], v[98:99], v[84:85] op_sel_hi:[1,0,1]
	v_and_b32_e32 v112, 0xffff0000, v109
	v_pk_add_f32 v[82:83], v[84:85], v[82:83]
	s_waitcnt lgkmcnt(1)
	v_pk_mul_f32 v[84:85], v[66:67], v[108:109] op_sel_hi:[1,0]
	v_lshlrev_b32_e32 v110, 16, v109
	v_pk_fma_f32 v[84:85], v[64:65], v[106:107], v[84:85] op_sel_hi:[1,0,1]
	s_nop 0
	v_pk_add_f32 v[82:83], v[84:85], v[82:83]
	s_waitcnt lgkmcnt(0)
	v_pk_mul_f32 v[84:85], v[62:63], v[112:113] op_sel_hi:[1,0]
	s_nop 0
	v_pk_fma_f32 v[84:85], v[60:61], v[110:111], v[84:85] op_sel_hi:[1,0,1]
	s_nop 0
	v_pk_add_f32 v[82:83], v[84:85], v[82:83]
	s_waitcnt vmcnt(15)
	v_mov_b64_e32 v[84:85], v[134:135]
	v_mov_b64_e32 v[86:87], v[136:137]
	global_load_dwordx4 v[134:137], v[190:191], off offset:512
	v_lshlrev_b32_e32 v98, 16, v84
	v_and_b32_e32 v84, 0xffff0000, v84
	v_lshlrev_b32_e32 v100, 16, v85
	v_and_b32_e32 v106, 0xffff0000, v85
	v_lshlrev_b32_e32 v108, 16, v86
	v_and_b32_e32 v86, 0xffff0000, v86
	v_pk_mul_f32 v[84:85], v[74:75], v[84:85] op_sel_hi:[1,0]
	v_lshlrev_b32_e32 v110, 16, v87
	v_and_b32_e32 v112, 0xffff0000, v87
	v_pk_fma_f32 v[84:85], v[72:73], v[98:99], v[84:85] op_sel_hi:[1,0,1]
	v_pk_mul_f32 v[86:87], v[66:67], v[86:87] op_sel_hi:[1,0]
	v_pk_add_f32 v[84:85], v[94:95], v[84:85]
	v_pk_mul_f32 v[94:95], v[70:71], v[106:107] op_sel_hi:[1,0]
	v_pk_fma_f32 v[86:87], v[64:65], v[108:109], v[86:87] op_sel_hi:[1,0,1]
	v_pk_fma_f32 v[94:95], v[68:69], v[100:101], v[94:95] op_sel_hi:[1,0,1]
	s_waitcnt vmcnt(15)
	v_mov_b64_e32 v[106:107], v[138:139]
	v_mov_b64_e32 v[108:109], v[140:141]
	global_load_dwordx4 v[138:141], v[192:193], off offset:512
	v_and_b32_e32 v100, 0xffff0000, v107
	v_pk_add_f32 v[84:85], v[94:95], v[84:85]
	v_and_b32_e32 v94, 0xffff0000, v106
	v_pk_add_f32 v[84:85], v[86:87], v[84:85]
	v_pk_mul_f32 v[86:87], v[62:63], v[112:113] op_sel_hi:[1,0]
	v_pk_mul_f32 v[94:95], v[74:75], v[94:95] op_sel_hi:[1,0]
	v_pk_fma_f32 v[86:87], v[60:61], v[110:111], v[86:87] op_sel_hi:[1,0,1]
	v_lshlrev_b32_e32 v98, 16, v107
	v_pk_add_f32 v[84:85], v[86:87], v[84:85]
	v_lshlrev_b32_e32 v86, 16, v106
	v_pk_fma_f32 v[86:87], v[72:73], v[86:87], v[94:95] op_sel_hi:[1,0,1]
	v_pk_mul_f32 v[94:95], v[70:71], v[100:101] op_sel_hi:[1,0]
	v_lshlrev_b32_e32 v106, 16, v108
	v_and_b32_e32 v108, 0xffff0000, v108
	v_pk_add_f32 v[86:87], v[96:97], v[86:87]
	v_pk_fma_f32 v[94:95], v[68:69], v[98:99], v[94:95] op_sel_hi:[1,0,1]
	v_and_b32_e32 v112, 0xffff0000, v109
	v_pk_add_f32 v[86:87], v[94:95], v[86:87]
	v_pk_mul_f32 v[94:95], v[66:67], v[108:109] op_sel_hi:[1,0]
	v_lshlrev_b32_e32 v110, 16, v109
	v_pk_fma_f32 v[94:95], v[64:65], v[106:107], v[94:95] op_sel_hi:[1,0,1]
	s_nop 0
	v_pk_add_f32 v[86:87], v[94:95], v[86:87]
	v_pk_mul_f32 v[94:95], v[62:63], v[112:113] op_sel_hi:[1,0]
	s_nop 0
	v_pk_fma_f32 v[94:95], v[60:61], v[110:111], v[94:95] op_sel_hi:[1,0,1]
	s_nop 0
	v_pk_add_f32 v[86:87], v[94:95], v[86:87]
	s_waitcnt vmcnt(15)
	v_mov_b64_e32 v[94:95], v[142:143]
	v_mov_b64_e32 v[96:97], v[144:145]
	global_load_dwordx4 v[142:145], v[194:195], off offset:512
	v_lshlrev_b32_e32 v98, 16, v94
	v_and_b32_e32 v94, 0xffff0000, v94
	v_lshlrev_b32_e32 v108, 16, v96
	v_and_b32_e32 v96, 0xffff0000, v96
	v_lshlrev_b32_e32 v100, 16, v95
	v_and_b32_e32 v106, 0xffff0000, v95
	v_lshlrev_b32_e32 v110, 16, v97
	v_and_b32_e32 v112, 0xffff0000, v97
	v_pk_mul_f32 v[74:75], v[74:75], v[94:95] op_sel_hi:[1,0]
	v_pk_mul_f32 v[66:67], v[66:67], v[96:97] op_sel_hi:[1,0]
	v_pk_fma_f32 v[72:73], v[72:73], v[98:99], v[74:75] op_sel_hi:[1,0,1]
	v_pk_mul_f32 v[70:71], v[70:71], v[106:107] op_sel_hi:[1,0]
	v_pk_add_f32 v[72:73], v[80:81], v[72:73]
	v_pk_fma_f32 v[68:69], v[68:69], v[100:101], v[70:71] op_sel_hi:[1,0,1]
	v_pk_fma_f32 v[64:65], v[64:65], v[108:109], v[66:67] op_sel_hi:[1,0,1]
	v_pk_add_f32 v[68:69], v[68:69], v[72:73]
	v_pk_mul_f32 v[62:63], v[62:63], v[112:113] op_sel_hi:[1,0]
	v_pk_add_f32 v[64:65], v[64:65], v[68:69]
	v_pk_fma_f32 v[60:61], v[60:61], v[110:111], v[62:63] op_sel_hi:[1,0,1]
	s_waitcnt vmcnt(15)
	v_mov_b64_e32 v[94:95], v[146:147]
	v_mov_b64_e32 v[96:97], v[148:149]
	global_load_dwordx4 v[146:149], v[188:189], off offset:768
	v_lshlrev_b32_e32 v98, 16, v94
	v_pk_add_f32 v[80:81], v[60:61], v[64:65]
	v_add_u32_e32 v60, 0x11800, v2
	ds_read_b128 v[72:75], v60
	v_add_u32_e32 v60, 0x11810, v2
	ds_read_b128 v[68:71], v60
	v_add_u32_e32 v60, 0x11820, v2
	ds_read_b128 v[64:67], v60
	v_and_b32_e32 v94, 0xffff0000, v94
	v_add_u32_e32 v60, 0x11830, v2
	v_lshlrev_b32_e32 v100, 16, v95
	v_and_b32_e32 v106, 0xffff0000, v95
	s_waitcnt lgkmcnt(2)
	v_pk_mul_f32 v[94:95], v[74:75], v[94:95] op_sel_hi:[1,0]
	ds_read_b128 v[60:63], v60
	v_pk_fma_f32 v[94:95], v[72:73], v[98:99], v[94:95] op_sel_hi:[1,0,1]
	v_lshlrev_b32_e32 v108, 16, v96
	v_pk_add_f32 v[82:83], v[82:83], v[94:95]
	s_waitcnt lgkmcnt(2)
	v_pk_mul_f32 v[94:95], v[70:71], v[106:107] op_sel_hi:[1,0]
	v_and_b32_e32 v96, 0xffff0000, v96
	v_pk_fma_f32 v[94:95], v[68:69], v[100:101], v[94:95] op_sel_hi:[1,0,1]
	v_and_b32_e32 v112, 0xffff0000, v97
	v_pk_add_f32 v[82:83], v[94:95], v[82:83]
	s_waitcnt lgkmcnt(1)
	v_pk_mul_f32 v[94:95], v[66:67], v[96:97] op_sel_hi:[1,0]
	v_lshlrev_b32_e32 v110, 16, v97
	v_pk_fma_f32 v[94:95], v[64:65], v[108:109], v[94:95] op_sel_hi:[1,0,1]
	s_nop 0
	v_pk_add_f32 v[82:83], v[94:95], v[82:83]
	s_waitcnt lgkmcnt(0)
	v_pk_mul_f32 v[94:95], v[62:63], v[112:113] op_sel_hi:[1,0]
	s_nop 0
	v_pk_fma_f32 v[94:95], v[60:61], v[110:111], v[94:95] op_sel_hi:[1,0,1]
	s_nop 0
	v_pk_add_f32 v[82:83], v[94:95], v[82:83]
	s_waitcnt vmcnt(15)
	v_mov_b64_e32 v[94:95], v[150:151]
	v_mov_b64_e32 v[96:97], v[152:153]
	global_load_dwordx4 v[150:153], v[190:191], off offset:768
	v_lshlrev_b32_e32 v98, 16, v94
	v_and_b32_e32 v94, 0xffff0000, v94
	v_lshlrev_b32_e32 v100, 16, v95
	v_and_b32_e32 v106, 0xffff0000, v95
	v_pk_mul_f32 v[94:95], v[74:75], v[94:95] op_sel_hi:[1,0]
	v_lshlrev_b32_e32 v108, 16, v96
	v_pk_fma_f32 v[94:95], v[72:73], v[98:99], v[94:95] op_sel_hi:[1,0,1]
	v_and_b32_e32 v96, 0xffff0000, v96
	v_pk_add_f32 v[84:85], v[84:85], v[94:95]
	v_pk_mul_f32 v[94:95], v[70:71], v[106:107] op_sel_hi:[1,0]
	v_and_b32_e32 v112, 0xffff0000, v97
	v_pk_fma_f32 v[94:95], v[68:69], v[100:101], v[94:95] op_sel_hi:[1,0,1]
	v_lshlrev_b32_e32 v110, 16, v97
	v_pk_add_f32 v[84:85], v[94:95], v[84:85]
	v_pk_mul_f32 v[94:95], v[66:67], v[96:97] op_sel_hi:[1,0]
	s_nop 0
	v_pk_fma_f32 v[94:95], v[64:65], v[108:109], v[94:95] op_sel_hi:[1,0,1]
	v_pk_add_f32 v[84:85], v[94:95], v[84:85]
	v_pk_mul_f32 v[94:95], v[62:63], v[112:113] op_sel_hi:[1,0]
	s_waitcnt vmcnt(15)
	v_mov_b64_e32 v[106:107], v[154:155]
	v_mov_b64_e32 v[108:109], v[156:157]
	global_load_dwordx4 v[154:157], v[192:193], off offset:768
	v_and_b32_e32 v96, 0xffff0000, v106
	v_pk_fma_f32 v[94:95], v[60:61], v[110:111], v[94:95] op_sel_hi:[1,0,1]
	v_pk_mul_f32 v[96:97], v[74:75], v[96:97] op_sel_hi:[1,0]
	v_pk_add_f32 v[94:95], v[94:95], v[84:85]
	v_lshlrev_b32_e32 v84, 16, v106
	v_and_b32_e32 v100, 0xffff0000, v107
	v_pk_fma_f32 v[84:85], v[72:73], v[84:85], v[96:97] op_sel_hi:[1,0,1]
	v_lshlrev_b32_e32 v98, 16, v107
	v_pk_add_f32 v[84:85], v[86:87], v[84:85]
	v_pk_mul_f32 v[86:87], v[70:71], v[100:101] op_sel_hi:[1,0]
	v_lshlrev_b32_e32 v106, 16, v108
	v_and_b32_e32 v108, 0xffff0000, v108
	v_pk_fma_f32 v[86:87], v[68:69], v[98:99], v[86:87] op_sel_hi:[1,0,1]
	v_and_b32_e32 v112, 0xffff0000, v109
	v_pk_add_f32 v[84:85], v[86:87], v[84:85]
	v_pk_mul_f32 v[86:87], v[66:67], v[108:109] op_sel_hi:[1,0]
	v_lshlrev_b32_e32 v110, 16, v109
	v_pk_fma_f32 v[86:87], v[64:65], v[106:107], v[86:87] op_sel_hi:[1,0,1]
	s_nop 0
	v_pk_add_f32 v[84:85], v[86:87], v[84:85]
	v_pk_mul_f32 v[86:87], v[62:63], v[112:113] op_sel_hi:[1,0]
	s_nop 0
	v_pk_fma_f32 v[86:87], v[60:61], v[110:111], v[86:87] op_sel_hi:[1,0,1]
	s_nop 0
	v_pk_add_f32 v[96:97], v[86:87], v[84:85]
	s_waitcnt vmcnt(15)
	v_mov_b64_e32 v[84:85], v[158:159]
	v_mov_b64_e32 v[86:87], v[160:161]
	global_load_dwordx4 v[158:161], v[194:195], off offset:768
	v_lshlrev_b32_e32 v108, 16, v86
	v_and_b32_e32 v86, 0xffff0000, v86
	v_and_b32_e32 v106, 0xffff0000, v85
	v_pk_mul_f32 v[66:67], v[66:67], v[86:87] op_sel_hi:[1,0]
	v_pk_mul_f32 v[70:71], v[70:71], v[106:107] op_sel_hi:[1,0]
	v_pk_fma_f32 v[64:65], v[64:65], v[108:109], v[66:67] op_sel_hi:[1,0,1]
	v_lshlrev_b32_e32 v98, 16, v84
	v_and_b32_e32 v84, 0xffff0000, v84
	v_pk_mul_f32 v[74:75], v[74:75], v[84:85] op_sel_hi:[1,0]
	v_lshlrev_b32_e32 v100, 16, v85
	v_pk_fma_f32 v[72:73], v[72:73], v[98:99], v[74:75] op_sel_hi:[1,0,1]
	v_and_b32_e32 v112, 0xffff0000, v87
	v_pk_add_f32 v[72:73], v[80:81], v[72:73]
	v_pk_fma_f32 v[68:69], v[68:69], v[100:101], v[70:71] op_sel_hi:[1,0,1]
	v_lshlrev_b32_e32 v110, 16, v87
	v_pk_add_f32 v[68:69], v[68:69], v[72:73]
	v_pk_mul_f32 v[62:63], v[62:63], v[112:113] op_sel_hi:[1,0]
	v_pk_add_f32 v[64:65], v[64:65], v[68:69]
	v_pk_fma_f32 v[60:61], v[60:61], v[110:111], v[62:63] op_sel_hi:[1,0,1]
	s_waitcnt vmcnt(15)
	v_mov_b64_e32 v[106:107], v[162:163]
	v_mov_b64_e32 v[108:109], v[164:165]
	global_load_dwordx4 v[162:165], v[188:189], off offset:1024
	v_and_b32_e32 v80, 0xffff0000, v106
	v_pk_add_f32 v[86:87], v[60:61], v[64:65]
	v_add_u32_e32 v60, 0x11c00, v2
	ds_read_b128 v[72:75], v60
	v_add_u32_e32 v60, 0x11c10, v2
	ds_read_b128 v[68:71], v60
	v_add_u32_e32 v60, 0x11c20, v2
	ds_read_b128 v[64:67], v60
	v_add_u32_e32 v2, 0x11c30, v2
	ds_read_b128 v[60:63], v2
	v_lshlrev_b32_e32 v2, 16, v106
	s_waitcnt lgkmcnt(3)
	v_pk_mul_f32 v[80:81], v[74:75], v[80:81] op_sel_hi:[1,0]
	v_and_b32_e32 v88, 0xffff0000, v107
	v_pk_fma_f32 v[80:81], v[72:73], v[2:3], v[80:81] op_sel_hi:[1,0,1]
	v_lshlrev_b32_e32 v84, 16, v107
	v_pk_add_f32 v[80:81], v[82:83], v[80:81]
	s_waitcnt lgkmcnt(2)
	v_pk_mul_f32 v[82:83], v[70:71], v[88:89] op_sel_hi:[1,0]
	v_and_b32_e32 v100, 0xffff0000, v108
	v_pk_fma_f32 v[82:83], v[68:69], v[84:85], v[82:83] op_sel_hi:[1,0,1]
	v_lshlrev_b32_e32 v98, 16, v108
	v_pk_add_f32 v[80:81], v[82:83], v[80:81]
	s_waitcnt lgkmcnt(1)
	v_pk_mul_f32 v[82:83], v[66:67], v[100:101] op_sel_hi:[1,0]
	v_and_b32_e32 v108, 0xffff0000, v109
	v_pk_fma_f32 v[82:83], v[64:65], v[98:99], v[82:83] op_sel_hi:[1,0,1]
	v_lshlrev_b32_e32 v106, 16, v109
	v_pk_add_f32 v[80:81], v[82:83], v[80:81]
	s_waitcnt lgkmcnt(0)
	v_pk_mul_f32 v[82:83], v[62:63], v[108:109] op_sel_hi:[1,0]
	s_nop 0
	v_pk_fma_f32 v[82:83], v[60:61], v[106:107], v[82:83] op_sel_hi:[1,0,1]
	s_nop 0
	v_pk_add_f32 v[84:85], v[82:83], v[80:81]
	s_waitcnt vmcnt(15)
	v_mov_b64_e32 v[80:81], v[176:177]
	v_mov_b64_e32 v[82:83], v[178:179]
	global_load_dwordx4 v[176:179], v[190:191], off offset:1024
	v_lshlrev_b32_e32 v2, 16, v80
	v_and_b32_e32 v80, 0xffff0000, v80
	v_lshlrev_b32_e32 v88, 16, v81
	v_and_b32_e32 v90, 0xffff0000, v81
	v_pk_mul_f32 v[80:81], v[74:75], v[80:81] op_sel_hi:[1,0]
	v_pk_mul_f32 v[90:91], v[70:71], v[90:91] op_sel_hi:[1,0]
	v_pk_fma_f32 v[80:81], v[72:73], v[2:3], v[80:81] op_sel_hi:[1,0,1]
	v_pk_fma_f32 v[88:89], v[68:69], v[88:89], v[90:91] op_sel_hi:[1,0,1]
	v_pk_add_f32 v[80:81], v[94:95], v[80:81]
	v_lshlrev_b32_e32 v98, 16, v82
	v_pk_add_f32 v[80:81], v[88:89], v[80:81]
	v_and_b32_e32 v82, 0xffff0000, v82
	v_lshlrev_b32_e32 v100, 16, v83
	v_and_b32_e32 v106, 0xffff0000, v83
	v_pk_mul_f32 v[82:83], v[66:67], v[82:83] op_sel_hi:[1,0]
	s_waitcnt vmcnt(15)
	v_mov_b64_e32 v[88:89], v[180:181]
	v_mov_b64_e32 v[90:91], v[182:183]
	global_load_dwordx4 v[180:183], v[192:193], off offset:1024
	v_lshlrev_b32_e32 v2, 16, v88
	v_pk_fma_f32 v[82:83], v[64:65], v[98:99], v[82:83] op_sel_hi:[1,0,1]
	v_and_b32_e32 v92, 0xffff0000, v89
	v_pk_add_f32 v[80:81], v[82:83], v[80:81]
	v_pk_mul_f32 v[82:83], v[62:63], v[106:107] op_sel_hi:[1,0]
	v_pk_mul_f32 v[92:93], v[70:71], v[92:93] op_sel_hi:[1,0]
	v_pk_fma_f32 v[82:83], v[60:61], v[100:101], v[82:83] op_sel_hi:[1,0,1]
	v_lshlrev_b32_e32 v94, 16, v90
	v_pk_add_f32 v[82:83], v[82:83], v[80:81]
	v_and_b32_e32 v80, 0xffff0000, v88
	v_pk_mul_f32 v[80:81], v[74:75], v[80:81] op_sel_hi:[1,0]
	v_lshlrev_b32_e32 v88, 16, v89
	v_pk_fma_f32 v[80:81], v[72:73], v[2:3], v[80:81] op_sel_hi:[1,0,1]
	v_and_b32_e32 v90, 0xffff0000, v90
	v_pk_add_f32 v[80:81], v[96:97], v[80:81]
	v_pk_fma_f32 v[88:89], v[68:69], v[88:89], v[92:93] op_sel_hi:[1,0,1]
	v_lshlrev_b32_e32 v98, 16, v91
	v_and_b32_e32 v100, 0xffff0000, v91
	v_pk_add_f32 v[80:81], v[88:89], v[80:81]
	v_pk_mul_f32 v[88:89], v[66:67], v[90:91] op_sel_hi:[1,0]
	v_pk_fma_f32 v[88:89], v[64:65], v[94:95], v[88:89] op_sel_hi:[1,0,1]
	v_lshl_add_u64 v[78:79], v[78:79], 0, s[6:7]
	v_pk_add_f32 v[80:81], v[88:89], v[80:81]
	v_pk_mul_f32 v[88:89], v[62:63], v[100:101] op_sel_hi:[1,0]
	s_waitcnt vmcnt(15)
	v_mov_b64_e32 v[90:91], v[184:185]
	v_mov_b64_e32 v[92:93], v[186:187]
	global_load_dwordx4 v[184:187], v[194:195], off offset:1024
	v_and_b32_e32 v100, 0xffff0000, v90
	v_pk_fma_f32 v[88:89], v[60:61], v[98:99], v[88:89] op_sel_hi:[1,0,1]
	v_lshlrev_b32_e32 v98, 16, v90
	v_and_b32_e32 v96, 0xffff0000, v91
	v_pk_mul_f32 v[74:75], v[74:75], v[100:101] op_sel_hi:[1,0]
	v_lshlrev_b32_e32 v94, 16, v91
	v_lshlrev_b32_e32 v90, 16, v92
	v_and_b32_e32 v92, 0xffff0000, v92
	v_pk_fma_f32 v[72:73], v[72:73], v[98:99], v[74:75] op_sel_hi:[1,0,1]
	v_pk_mul_f32 v[70:71], v[70:71], v[96:97] op_sel_hi:[1,0]
	v_pk_add_f32 v[80:81], v[88:89], v[80:81]
	v_and_b32_e32 v88, 0xffff0000, v93
	v_pk_add_f32 v[72:73], v[86:87], v[72:73]
	v_pk_fma_f32 v[68:69], v[68:69], v[94:95], v[70:71] op_sel_hi:[1,0,1]
	v_pk_mul_f32 v[66:67], v[66:67], v[92:93] op_sel_hi:[1,0]
	v_lshlrev_b32_e32 v2, 16, v93
	v_pk_add_f32 v[68:69], v[68:69], v[72:73]
	v_pk_fma_f32 v[64:65], v[64:65], v[90:91], v[66:67] op_sel_hi:[1,0,1]
	v_pk_mul_f32 v[62:63], v[62:63], v[88:89] op_sel_hi:[1,0]
	v_pk_add_f32 v[64:65], v[64:65], v[68:69]
	v_pk_fma_f32 v[60:61], v[60:61], v[2:3], v[62:63] op_sel_hi:[1,0,1]
	s_nop 0
	v_pk_add_f32 v[86:87], v[60:61], v[64:65]
	s_mov_b32 s5, 0xfffd0000
	v_add_co_u32_e32 v88, vcc, s5, v78
	v_add_u32_e32 v2, s4, v104
	s_nop 0
	v_addc_co_u32_e32 v89, vcc, -1, v79, vcc
	v_add_u32_e32 v60, 0x11000, v2
	ds_read_b128 v[72:75], v60
	v_add_u32_e32 v60, 0x11010, v2
	ds_read_b128 v[68:71], v60
	v_add_u32_e32 v60, 0x11020, v2
	ds_read_b128 v[64:67], v60
	v_add_u32_e32 v60, 0x11030, v2
	ds_read_b128 v[60:63], v60
	s_mov_b32 s5, 0xfffe0000
	s_addk_i32 s4, 0x1000
	s_mov_b64 s[6:7], 0x400
	s_cmpk_eq_i32 s4, 0x2000
	s_waitcnt vmcnt(15)
	v_mov_b64_e32 v[90:91], v[114:115]
	v_mov_b64_e32 v[92:93], v[116:117]
	v_lshlrev_b32_e32 v94, 16, v90
	v_and_b32_e32 v90, 0xffff0000, v90
	v_lshlrev_b32_e32 v96, 16, v91
	v_and_b32_e32 v98, 0xffff0000, v91
	s_waitcnt lgkmcnt(3)
	v_pk_mul_f32 v[90:91], v[74:75], v[90:91] op_sel_hi:[1,0]
	v_lshlrev_b32_e32 v100, 16, v92
	v_pk_fma_f32 v[90:91], v[72:73], v[94:95], v[90:91] op_sel_hi:[1,0,1]
	v_and_b32_e32 v92, 0xffff0000, v92
	v_pk_add_f32 v[84:85], v[84:85], v[90:91]
	s_waitcnt lgkmcnt(2)
	v_pk_mul_f32 v[90:91], v[70:71], v[98:99] op_sel_hi:[1,0]
	v_and_b32_e32 v108, 0xffff0000, v93
	v_pk_fma_f32 v[90:91], v[68:69], v[96:97], v[90:91] op_sel_hi:[1,0,1]
	v_lshlrev_b32_e32 v106, 16, v93
	v_pk_add_f32 v[84:85], v[90:91], v[84:85]
	s_waitcnt lgkmcnt(1)
	v_pk_mul_f32 v[90:91], v[66:67], v[92:93] op_sel_hi:[1,0]
	s_nop 0
	v_pk_fma_f32 v[90:91], v[64:65], v[100:101], v[90:91] op_sel_hi:[1,0,1]
	s_nop 0
	v_pk_add_f32 v[84:85], v[90:91], v[84:85]
	s_waitcnt lgkmcnt(0)
	v_pk_mul_f32 v[90:91], v[62:63], v[108:109] op_sel_hi:[1,0]
	s_nop 0
	v_pk_fma_f32 v[90:91], v[60:61], v[106:107], v[90:91] op_sel_hi:[1,0,1]
	s_nop 0
	v_pk_add_f32 v[84:85], v[90:91], v[84:85]
	v_add_co_u32_e32 v90, vcc, s5, v78
	s_nop 1
	v_addc_co_u32_e32 v91, vcc, -1, v79, vcc
	s_waitcnt vmcnt(14)
	v_mov_b64_e32 v[92:93], v[118:119]
	v_mov_b64_e32 v[94:95], v[120:121]
	v_lshlrev_b32_e32 v96, 16, v92
	v_and_b32_e32 v92, 0xffff0000, v92
	v_lshlrev_b32_e32 v98, 16, v93
	v_and_b32_e32 v100, 0xffff0000, v93
	v_pk_mul_f32 v[92:93], v[74:75], v[92:93] op_sel_hi:[1,0]
	v_lshlrev_b32_e32 v106, 16, v94
	v_pk_fma_f32 v[92:93], v[72:73], v[96:97], v[92:93] op_sel_hi:[1,0,1]
	v_and_b32_e32 v94, 0xffff0000, v94
	v_pk_add_f32 v[82:83], v[82:83], v[92:93]
	v_pk_mul_f32 v[92:93], v[70:71], v[100:101] op_sel_hi:[1,0]
	v_and_b32_e32 v110, 0xffff0000, v95
	v_pk_fma_f32 v[92:93], v[68:69], v[98:99], v[92:93] op_sel_hi:[1,0,1]
	v_lshlrev_b32_e32 v108, 16, v95
	v_pk_add_f32 v[82:83], v[92:93], v[82:83]
	v_pk_mul_f32 v[92:93], v[66:67], v[94:95] op_sel_hi:[1,0]
	s_nop 0
	v_pk_fma_f32 v[92:93], v[64:65], v[106:107], v[92:93] op_sel_hi:[1,0,1]
	s_nop 0
	v_pk_add_f32 v[82:83], v[92:93], v[82:83]
	v_pk_mul_f32 v[92:93], v[62:63], v[110:111] op_sel_hi:[1,0]
	s_nop 0
	v_pk_fma_f32 v[92:93], v[60:61], v[108:109], v[92:93] op_sel_hi:[1,0,1]
	s_nop 0
	v_pk_add_f32 v[94:95], v[92:93], v[82:83]
	v_add_co_u32_e32 v92, vcc, s33, v78
	s_nop 1
	v_addc_co_u32_e32 v93, vcc, -1, v79, vcc
	s_waitcnt vmcnt(13)
	v_mov_b64_e32 v[106:107], v[122:123]
	v_mov_b64_e32 v[108:109], v[124:125]
	v_and_b32_e32 v96, 0xffff0000, v106
	v_lshlrev_b32_e32 v82, 16, v106
	v_pk_mul_f32 v[96:97], v[74:75], v[96:97] op_sel_hi:[1,0]
	v_and_b32_e32 v100, 0xffff0000, v107
	v_pk_fma_f32 v[82:83], v[72:73], v[82:83], v[96:97] op_sel_hi:[1,0,1]
	v_lshlrev_b32_e32 v98, 16, v107
	v_pk_add_f32 v[80:81], v[80:81], v[82:83]
	v_pk_mul_f32 v[82:83], v[70:71], v[100:101] op_sel_hi:[1,0]
	v_lshlrev_b32_e32 v106, 16, v108
	v_and_b32_e32 v108, 0xffff0000, v108
	v_pk_fma_f32 v[82:83], v[68:69], v[98:99], v[82:83] op_sel_hi:[1,0,1]
	v_and_b32_e32 v112, 0xffff0000, v109
	v_pk_add_f32 v[80:81], v[82:83], v[80:81]
	v_pk_mul_f32 v[82:83], v[66:67], v[108:109] op_sel_hi:[1,0]
	v_lshlrev_b32_e32 v110, 16, v109
	v_pk_fma_f32 v[82:83], v[64:65], v[106:107], v[82:83] op_sel_hi:[1,0,1]
	s_nop 0
	v_pk_add_f32 v[80:81], v[82:83], v[80:81]
	v_pk_mul_f32 v[82:83], v[62:63], v[112:113] op_sel_hi:[1,0]
	s_nop 0
	v_pk_fma_f32 v[82:83], v[60:61], v[110:111], v[82:83] op_sel_hi:[1,0,1]
	s_nop 0
	v_pk_add_f32 v[96:97], v[82:83], v[80:81]
	s_waitcnt vmcnt(12)
	v_mov_b64_e32 v[80:81], v[126:127]
	v_mov_b64_e32 v[82:83], v[128:129]
	v_lshlrev_b32_e32 v108, 16, v82
	v_and_b32_e32 v82, 0xffff0000, v82
	v_and_b32_e32 v106, 0xffff0000, v81
	v_pk_mul_f32 v[66:67], v[66:67], v[82:83] op_sel_hi:[1,0]
	v_pk_mul_f32 v[70:71], v[70:71], v[106:107] op_sel_hi:[1,0]
	v_pk_fma_f32 v[64:65], v[64:65], v[108:109], v[66:67] op_sel_hi:[1,0,1]
	v_lshlrev_b32_e32 v98, 16, v80
	v_and_b32_e32 v80, 0xffff0000, v80
	v_pk_mul_f32 v[74:75], v[74:75], v[80:81] op_sel_hi:[1,0]
	v_lshlrev_b32_e32 v100, 16, v81
	v_pk_fma_f32 v[72:73], v[72:73], v[98:99], v[74:75] op_sel_hi:[1,0,1]
	v_and_b32_e32 v112, 0xffff0000, v83
	v_pk_add_f32 v[72:73], v[86:87], v[72:73]
	v_pk_fma_f32 v[68:69], v[68:69], v[100:101], v[70:71] op_sel_hi:[1,0,1]
	v_lshlrev_b32_e32 v110, 16, v83
	v_pk_add_f32 v[68:69], v[68:69], v[72:73]
	v_pk_mul_f32 v[62:63], v[62:63], v[112:113] op_sel_hi:[1,0]
	v_pk_add_f32 v[64:65], v[64:65], v[68:69]
	v_pk_fma_f32 v[60:61], v[60:61], v[110:111], v[62:63] op_sel_hi:[1,0,1]
	s_waitcnt vmcnt(11)
	v_mov_b64_e32 v[106:107], v[130:131]
	v_mov_b64_e32 v[108:109], v[132:133]
	v_and_b32_e32 v86, 0xffff0000, v106
	v_pk_add_f32 v[80:81], v[60:61], v[64:65]
	v_add_u32_e32 v60, 0x11400, v2
	ds_read_b128 v[72:75], v60
	v_add_u32_e32 v60, 0x11410, v2
	ds_read_b128 v[68:71], v60
	v_add_u32_e32 v60, 0x11420, v2
	ds_read_b128 v[64:67], v60
	v_add_u32_e32 v60, 0x11430, v2
	v_lshlrev_b32_e32 v82, 16, v106
	s_waitcnt lgkmcnt(2)
	v_pk_mul_f32 v[86:87], v[74:75], v[86:87] op_sel_hi:[1,0]
	ds_read_b128 v[60:63], v60
	v_and_b32_e32 v100, 0xffff0000, v107
	v_pk_fma_f32 v[82:83], v[72:73], v[82:83], v[86:87] op_sel_hi:[1,0,1]
	v_lshlrev_b32_e32 v98, 16, v107
	v_pk_add_f32 v[82:83], v[84:85], v[82:83]
	s_waitcnt lgkmcnt(2)
	v_pk_mul_f32 v[84:85], v[70:71], v[100:101] op_sel_hi:[1,0]
	v_lshlrev_b32_e32 v106, 16, v108
	v_and_b32_e32 v108, 0xffff0000, v108
	v_pk_fma_f32 v[84:85], v[68:69], v[98:99], v[84:85] op_sel_hi:[1,0,1]
	v_and_b32_e32 v112, 0xffff0000, v109
	v_pk_add_f32 v[82:83], v[84:85], v[82:83]
	s_waitcnt lgkmcnt(1)
	v_pk_mul_f32 v[84:85], v[66:67], v[108:109] op_sel_hi:[1,0]
	v_lshlrev_b32_e32 v110, 16, v109
	v_pk_fma_f32 v[84:85], v[64:65], v[106:107], v[84:85] op_sel_hi:[1,0,1]
	s_nop 0
	v_pk_add_f32 v[82:83], v[84:85], v[82:83]
	s_waitcnt lgkmcnt(0)
	v_pk_mul_f32 v[84:85], v[62:63], v[112:113] op_sel_hi:[1,0]
	s_nop 0
	v_pk_fma_f32 v[84:85], v[60:61], v[110:111], v[84:85] op_sel_hi:[1,0,1]
	s_nop 0
	v_pk_add_f32 v[82:83], v[84:85], v[82:83]
	s_waitcnt vmcnt(10)
	v_mov_b64_e32 v[84:85], v[134:135]
	v_mov_b64_e32 v[86:87], v[136:137]
	v_lshlrev_b32_e32 v98, 16, v84
	v_and_b32_e32 v84, 0xffff0000, v84
	v_lshlrev_b32_e32 v100, 16, v85
	v_and_b32_e32 v106, 0xffff0000, v85
	v_lshlrev_b32_e32 v108, 16, v86
	v_and_b32_e32 v86, 0xffff0000, v86
	v_pk_mul_f32 v[84:85], v[74:75], v[84:85] op_sel_hi:[1,0]
	v_lshlrev_b32_e32 v110, 16, v87
	v_and_b32_e32 v112, 0xffff0000, v87
	v_pk_fma_f32 v[84:85], v[72:73], v[98:99], v[84:85] op_sel_hi:[1,0,1]
	v_pk_mul_f32 v[86:87], v[66:67], v[86:87] op_sel_hi:[1,0]
	v_pk_add_f32 v[84:85], v[94:95], v[84:85]
	v_pk_mul_f32 v[94:95], v[70:71], v[106:107] op_sel_hi:[1,0]
	v_pk_fma_f32 v[86:87], v[64:65], v[108:109], v[86:87] op_sel_hi:[1,0,1]
	v_pk_fma_f32 v[94:95], v[68:69], v[100:101], v[94:95] op_sel_hi:[1,0,1]
	s_waitcnt vmcnt(9)
	v_mov_b64_e32 v[106:107], v[138:139]
	v_mov_b64_e32 v[108:109], v[140:141]
	v_and_b32_e32 v100, 0xffff0000, v107
	v_pk_add_f32 v[84:85], v[94:95], v[84:85]
	v_and_b32_e32 v94, 0xffff0000, v106
	v_pk_add_f32 v[84:85], v[86:87], v[84:85]
	v_pk_mul_f32 v[86:87], v[62:63], v[112:113] op_sel_hi:[1,0]
	v_pk_mul_f32 v[94:95], v[74:75], v[94:95] op_sel_hi:[1,0]
	v_pk_fma_f32 v[86:87], v[60:61], v[110:111], v[86:87] op_sel_hi:[1,0,1]
	v_lshlrev_b32_e32 v98, 16, v107
	v_pk_add_f32 v[84:85], v[86:87], v[84:85]
	v_lshlrev_b32_e32 v86, 16, v106
	v_pk_fma_f32 v[86:87], v[72:73], v[86:87], v[94:95] op_sel_hi:[1,0,1]
	v_pk_mul_f32 v[94:95], v[70:71], v[100:101] op_sel_hi:[1,0]
	v_lshlrev_b32_e32 v106, 16, v108
	v_and_b32_e32 v108, 0xffff0000, v108
	v_pk_add_f32 v[86:87], v[96:97], v[86:87]
	v_pk_fma_f32 v[94:95], v[68:69], v[98:99], v[94:95] op_sel_hi:[1,0,1]
	v_and_b32_e32 v112, 0xffff0000, v109
	v_pk_add_f32 v[86:87], v[94:95], v[86:87]
	v_pk_mul_f32 v[94:95], v[66:67], v[108:109] op_sel_hi:[1,0]
	v_lshlrev_b32_e32 v110, 16, v109
	v_pk_fma_f32 v[94:95], v[64:65], v[106:107], v[94:95] op_sel_hi:[1,0,1]
	s_nop 0
	v_pk_add_f32 v[86:87], v[94:95], v[86:87]
	v_pk_mul_f32 v[94:95], v[62:63], v[112:113] op_sel_hi:[1,0]
	s_nop 0
	v_pk_fma_f32 v[94:95], v[60:61], v[110:111], v[94:95] op_sel_hi:[1,0,1]
	s_nop 0
	v_pk_add_f32 v[86:87], v[94:95], v[86:87]
	s_waitcnt vmcnt(8)
	v_mov_b64_e32 v[94:95], v[142:143]
	v_mov_b64_e32 v[96:97], v[144:145]
	v_lshlrev_b32_e32 v98, 16, v94
	v_and_b32_e32 v94, 0xffff0000, v94
	v_lshlrev_b32_e32 v108, 16, v96
	v_and_b32_e32 v96, 0xffff0000, v96
	v_lshlrev_b32_e32 v100, 16, v95
	v_and_b32_e32 v106, 0xffff0000, v95
	v_lshlrev_b32_e32 v110, 16, v97
	v_and_b32_e32 v112, 0xffff0000, v97
	v_pk_mul_f32 v[74:75], v[74:75], v[94:95] op_sel_hi:[1,0]
	v_pk_mul_f32 v[66:67], v[66:67], v[96:97] op_sel_hi:[1,0]
	v_pk_fma_f32 v[72:73], v[72:73], v[98:99], v[74:75] op_sel_hi:[1,0,1]
	v_pk_mul_f32 v[70:71], v[70:71], v[106:107] op_sel_hi:[1,0]
	v_pk_add_f32 v[72:73], v[80:81], v[72:73]
	v_pk_fma_f32 v[68:69], v[68:69], v[100:101], v[70:71] op_sel_hi:[1,0,1]
	v_pk_fma_f32 v[64:65], v[64:65], v[108:109], v[66:67] op_sel_hi:[1,0,1]
	v_pk_add_f32 v[68:69], v[68:69], v[72:73]
	v_pk_mul_f32 v[62:63], v[62:63], v[112:113] op_sel_hi:[1,0]
	v_pk_add_f32 v[64:65], v[64:65], v[68:69]
	v_pk_fma_f32 v[60:61], v[60:61], v[110:111], v[62:63] op_sel_hi:[1,0,1]
	s_waitcnt vmcnt(7)
	v_mov_b64_e32 v[94:95], v[146:147]
	v_mov_b64_e32 v[96:97], v[148:149]
	v_lshlrev_b32_e32 v98, 16, v94
	v_pk_add_f32 v[80:81], v[60:61], v[64:65]
	v_add_u32_e32 v60, 0x11800, v2
	ds_read_b128 v[72:75], v60
	v_add_u32_e32 v60, 0x11810, v2
	ds_read_b128 v[68:71], v60
	v_add_u32_e32 v60, 0x11820, v2
	ds_read_b128 v[64:67], v60
	v_and_b32_e32 v94, 0xffff0000, v94
	v_add_u32_e32 v60, 0x11830, v2
	v_lshlrev_b32_e32 v100, 16, v95
	v_and_b32_e32 v106, 0xffff0000, v95
	s_waitcnt lgkmcnt(2)
	v_pk_mul_f32 v[94:95], v[74:75], v[94:95] op_sel_hi:[1,0]
	ds_read_b128 v[60:63], v60
	v_pk_fma_f32 v[94:95], v[72:73], v[98:99], v[94:95] op_sel_hi:[1,0,1]
	v_lshlrev_b32_e32 v108, 16, v96
	v_pk_add_f32 v[82:83], v[82:83], v[94:95]
	s_waitcnt lgkmcnt(2)
	v_pk_mul_f32 v[94:95], v[70:71], v[106:107] op_sel_hi:[1,0]
	v_and_b32_e32 v96, 0xffff0000, v96
	v_pk_fma_f32 v[94:95], v[68:69], v[100:101], v[94:95] op_sel_hi:[1,0,1]
	v_and_b32_e32 v112, 0xffff0000, v97
	v_pk_add_f32 v[82:83], v[94:95], v[82:83]
	s_waitcnt lgkmcnt(1)
	v_pk_mul_f32 v[94:95], v[66:67], v[96:97] op_sel_hi:[1,0]
	v_lshlrev_b32_e32 v110, 16, v97
	v_pk_fma_f32 v[94:95], v[64:65], v[108:109], v[94:95] op_sel_hi:[1,0,1]
	s_nop 0
	v_pk_add_f32 v[82:83], v[94:95], v[82:83]
	s_waitcnt lgkmcnt(0)
	v_pk_mul_f32 v[94:95], v[62:63], v[112:113] op_sel_hi:[1,0]
	s_nop 0
	v_pk_fma_f32 v[94:95], v[60:61], v[110:111], v[94:95] op_sel_hi:[1,0,1]
	s_nop 0
	v_pk_add_f32 v[82:83], v[94:95], v[82:83]
	s_waitcnt vmcnt(6)
	v_mov_b64_e32 v[94:95], v[150:151]
	v_mov_b64_e32 v[96:97], v[152:153]
	v_lshlrev_b32_e32 v98, 16, v94
	v_and_b32_e32 v94, 0xffff0000, v94
	v_lshlrev_b32_e32 v100, 16, v95
	v_and_b32_e32 v106, 0xffff0000, v95
	v_pk_mul_f32 v[94:95], v[74:75], v[94:95] op_sel_hi:[1,0]
	v_lshlrev_b32_e32 v108, 16, v96
	v_pk_fma_f32 v[94:95], v[72:73], v[98:99], v[94:95] op_sel_hi:[1,0,1]
	v_and_b32_e32 v96, 0xffff0000, v96
	v_pk_add_f32 v[84:85], v[84:85], v[94:95]
	v_pk_mul_f32 v[94:95], v[70:71], v[106:107] op_sel_hi:[1,0]
	v_and_b32_e32 v112, 0xffff0000, v97
	v_pk_fma_f32 v[94:95], v[68:69], v[100:101], v[94:95] op_sel_hi:[1,0,1]
	v_lshlrev_b32_e32 v110, 16, v97
	v_pk_add_f32 v[84:85], v[94:95], v[84:85]
	v_pk_mul_f32 v[94:95], v[66:67], v[96:97] op_sel_hi:[1,0]
	s_nop 0
	v_pk_fma_f32 v[94:95], v[64:65], v[108:109], v[94:95] op_sel_hi:[1,0,1]
	v_pk_add_f32 v[84:85], v[94:95], v[84:85]
	v_pk_mul_f32 v[94:95], v[62:63], v[112:113] op_sel_hi:[1,0]
	s_waitcnt vmcnt(5)
	v_mov_b64_e32 v[106:107], v[154:155]
	v_mov_b64_e32 v[108:109], v[156:157]
	v_and_b32_e32 v96, 0xffff0000, v106
	v_pk_fma_f32 v[94:95], v[60:61], v[110:111], v[94:95] op_sel_hi:[1,0,1]
	v_pk_mul_f32 v[96:97], v[74:75], v[96:97] op_sel_hi:[1,0]
	v_pk_add_f32 v[94:95], v[94:95], v[84:85]
	v_lshlrev_b32_e32 v84, 16, v106
	v_and_b32_e32 v100, 0xffff0000, v107
	v_pk_fma_f32 v[84:85], v[72:73], v[84:85], v[96:97] op_sel_hi:[1,0,1]
	v_lshlrev_b32_e32 v98, 16, v107
	v_pk_add_f32 v[84:85], v[86:87], v[84:85]
	v_pk_mul_f32 v[86:87], v[70:71], v[100:101] op_sel_hi:[1,0]
	v_lshlrev_b32_e32 v106, 16, v108
	v_and_b32_e32 v108, 0xffff0000, v108
	v_pk_fma_f32 v[86:87], v[68:69], v[98:99], v[86:87] op_sel_hi:[1,0,1]
	v_and_b32_e32 v112, 0xffff0000, v109
	v_pk_add_f32 v[84:85], v[86:87], v[84:85]
	v_pk_mul_f32 v[86:87], v[66:67], v[108:109] op_sel_hi:[1,0]
	v_lshlrev_b32_e32 v110, 16, v109
	v_pk_fma_f32 v[86:87], v[64:65], v[106:107], v[86:87] op_sel_hi:[1,0,1]
	s_nop 0
	v_pk_add_f32 v[84:85], v[86:87], v[84:85]
	v_pk_mul_f32 v[86:87], v[62:63], v[112:113] op_sel_hi:[1,0]
	s_nop 0
	v_pk_fma_f32 v[86:87], v[60:61], v[110:111], v[86:87] op_sel_hi:[1,0,1]
	s_nop 0
	v_pk_add_f32 v[96:97], v[86:87], v[84:85]
	s_waitcnt vmcnt(4)
	v_mov_b64_e32 v[84:85], v[158:159]
	v_mov_b64_e32 v[86:87], v[160:161]
	v_lshlrev_b32_e32 v108, 16, v86
	v_and_b32_e32 v86, 0xffff0000, v86
	v_and_b32_e32 v106, 0xffff0000, v85
	v_pk_mul_f32 v[66:67], v[66:67], v[86:87] op_sel_hi:[1,0]
	v_pk_mul_f32 v[70:71], v[70:71], v[106:107] op_sel_hi:[1,0]
	v_pk_fma_f32 v[64:65], v[64:65], v[108:109], v[66:67] op_sel_hi:[1,0,1]
	v_lshlrev_b32_e32 v98, 16, v84
	v_and_b32_e32 v84, 0xffff0000, v84
	v_pk_mul_f32 v[74:75], v[74:75], v[84:85] op_sel_hi:[1,0]
	v_lshlrev_b32_e32 v100, 16, v85
	v_pk_fma_f32 v[72:73], v[72:73], v[98:99], v[74:75] op_sel_hi:[1,0,1]
	v_and_b32_e32 v112, 0xffff0000, v87
	v_pk_add_f32 v[72:73], v[80:81], v[72:73]
	v_pk_fma_f32 v[68:69], v[68:69], v[100:101], v[70:71] op_sel_hi:[1,0,1]
	v_lshlrev_b32_e32 v110, 16, v87
	v_pk_add_f32 v[68:69], v[68:69], v[72:73]
	v_pk_mul_f32 v[62:63], v[62:63], v[112:113] op_sel_hi:[1,0]
	v_pk_add_f32 v[64:65], v[64:65], v[68:69]
	v_pk_fma_f32 v[60:61], v[60:61], v[110:111], v[62:63] op_sel_hi:[1,0,1]
	s_waitcnt vmcnt(3)
	v_mov_b64_e32 v[106:107], v[162:163]
	v_mov_b64_e32 v[108:109], v[164:165]
	v_and_b32_e32 v80, 0xffff0000, v106
	v_pk_add_f32 v[86:87], v[60:61], v[64:65]
	v_add_u32_e32 v60, 0x11c00, v2
	ds_read_b128 v[72:75], v60
	v_add_u32_e32 v60, 0x11c10, v2
	ds_read_b128 v[68:71], v60
	v_add_u32_e32 v60, 0x11c20, v2
	ds_read_b128 v[64:67], v60
	v_add_u32_e32 v2, 0x11c30, v2
	ds_read_b128 v[60:63], v2
	v_lshlrev_b32_e32 v2, 16, v106
	s_waitcnt lgkmcnt(3)
	v_pk_mul_f32 v[80:81], v[74:75], v[80:81] op_sel_hi:[1,0]
	v_and_b32_e32 v88, 0xffff0000, v107
	v_pk_fma_f32 v[80:81], v[72:73], v[2:3], v[80:81] op_sel_hi:[1,0,1]
	v_lshlrev_b32_e32 v84, 16, v107
	v_pk_add_f32 v[80:81], v[82:83], v[80:81]
	s_waitcnt lgkmcnt(2)
	v_pk_mul_f32 v[82:83], v[70:71], v[88:89] op_sel_hi:[1,0]
	v_and_b32_e32 v100, 0xffff0000, v108
	v_pk_fma_f32 v[82:83], v[68:69], v[84:85], v[82:83] op_sel_hi:[1,0,1]
	v_lshlrev_b32_e32 v98, 16, v108
	v_pk_add_f32 v[80:81], v[82:83], v[80:81]
	s_waitcnt lgkmcnt(1)
	v_pk_mul_f32 v[82:83], v[66:67], v[100:101] op_sel_hi:[1,0]
	v_and_b32_e32 v108, 0xffff0000, v109
	v_pk_fma_f32 v[82:83], v[64:65], v[98:99], v[82:83] op_sel_hi:[1,0,1]
	v_lshlrev_b32_e32 v106, 16, v109
	v_pk_add_f32 v[80:81], v[82:83], v[80:81]
	s_waitcnt lgkmcnt(0)
	v_pk_mul_f32 v[82:83], v[62:63], v[108:109] op_sel_hi:[1,0]
	s_nop 0
	v_pk_fma_f32 v[82:83], v[60:61], v[106:107], v[82:83] op_sel_hi:[1,0,1]
	s_nop 0
	v_pk_add_f32 v[84:85], v[82:83], v[80:81]
	s_waitcnt vmcnt(2)
	v_mov_b64_e32 v[80:81], v[176:177]
	v_mov_b64_e32 v[82:83], v[178:179]
	v_lshlrev_b32_e32 v2, 16, v80
	v_and_b32_e32 v80, 0xffff0000, v80
	v_lshlrev_b32_e32 v88, 16, v81
	v_and_b32_e32 v90, 0xffff0000, v81
	v_pk_mul_f32 v[80:81], v[74:75], v[80:81] op_sel_hi:[1,0]
	v_pk_mul_f32 v[90:91], v[70:71], v[90:91] op_sel_hi:[1,0]
	v_pk_fma_f32 v[80:81], v[72:73], v[2:3], v[80:81] op_sel_hi:[1,0,1]
	v_pk_fma_f32 v[88:89], v[68:69], v[88:89], v[90:91] op_sel_hi:[1,0,1]
	v_pk_add_f32 v[80:81], v[94:95], v[80:81]
	v_lshlrev_b32_e32 v98, 16, v82
	v_pk_add_f32 v[80:81], v[88:89], v[80:81]
	v_and_b32_e32 v82, 0xffff0000, v82
	v_lshlrev_b32_e32 v100, 16, v83
	v_and_b32_e32 v106, 0xffff0000, v83
	v_pk_mul_f32 v[82:83], v[66:67], v[82:83] op_sel_hi:[1,0]
	s_waitcnt vmcnt(1)
	v_mov_b64_e32 v[88:89], v[180:181]
	v_mov_b64_e32 v[90:91], v[182:183]
	v_lshlrev_b32_e32 v2, 16, v88
	v_pk_fma_f32 v[82:83], v[64:65], v[98:99], v[82:83] op_sel_hi:[1,0,1]
	v_and_b32_e32 v92, 0xffff0000, v89
	v_pk_add_f32 v[80:81], v[82:83], v[80:81]
	v_pk_mul_f32 v[82:83], v[62:63], v[106:107] op_sel_hi:[1,0]
	v_pk_mul_f32 v[92:93], v[70:71], v[92:93] op_sel_hi:[1,0]
	v_pk_fma_f32 v[82:83], v[60:61], v[100:101], v[82:83] op_sel_hi:[1,0,1]
	v_lshlrev_b32_e32 v94, 16, v90
	v_pk_add_f32 v[82:83], v[82:83], v[80:81]
	v_and_b32_e32 v80, 0xffff0000, v88
	v_pk_mul_f32 v[80:81], v[74:75], v[80:81] op_sel_hi:[1,0]
	v_lshlrev_b32_e32 v88, 16, v89
	v_pk_fma_f32 v[80:81], v[72:73], v[2:3], v[80:81] op_sel_hi:[1,0,1]
	v_and_b32_e32 v90, 0xffff0000, v90
	v_pk_add_f32 v[80:81], v[96:97], v[80:81]
	v_pk_fma_f32 v[88:89], v[68:69], v[88:89], v[92:93] op_sel_hi:[1,0,1]
	v_lshlrev_b32_e32 v98, 16, v91
	v_and_b32_e32 v100, 0xffff0000, v91
	v_pk_add_f32 v[80:81], v[88:89], v[80:81]
	v_pk_mul_f32 v[88:89], v[66:67], v[90:91] op_sel_hi:[1,0]
	v_pk_fma_f32 v[88:89], v[64:65], v[94:95], v[88:89] op_sel_hi:[1,0,1]
	v_lshl_add_u64 v[78:79], v[78:79], 0, s[6:7]
	v_pk_add_f32 v[80:81], v[88:89], v[80:81]
	v_pk_mul_f32 v[88:89], v[62:63], v[100:101] op_sel_hi:[1,0]
	s_waitcnt vmcnt(0)
	v_mov_b64_e32 v[90:91], v[184:185]
	v_mov_b64_e32 v[92:93], v[186:187]
	v_and_b32_e32 v100, 0xffff0000, v90
	v_pk_fma_f32 v[88:89], v[60:61], v[98:99], v[88:89] op_sel_hi:[1,0,1]
	v_lshlrev_b32_e32 v98, 16, v90
	v_and_b32_e32 v96, 0xffff0000, v91
	v_pk_mul_f32 v[74:75], v[74:75], v[100:101] op_sel_hi:[1,0]
	v_lshlrev_b32_e32 v94, 16, v91
	v_lshlrev_b32_e32 v90, 16, v92
	v_and_b32_e32 v92, 0xffff0000, v92
	v_pk_fma_f32 v[72:73], v[72:73], v[98:99], v[74:75] op_sel_hi:[1,0,1]
	v_pk_mul_f32 v[70:71], v[70:71], v[96:97] op_sel_hi:[1,0]
	v_pk_add_f32 v[80:81], v[88:89], v[80:81]
	v_and_b32_e32 v88, 0xffff0000, v93
	v_pk_add_f32 v[72:73], v[86:87], v[72:73]
	v_pk_fma_f32 v[68:69], v[68:69], v[94:95], v[70:71] op_sel_hi:[1,0,1]
	v_pk_mul_f32 v[66:67], v[66:67], v[92:93] op_sel_hi:[1,0]
	v_lshlrev_b32_e32 v2, 16, v93
	v_pk_add_f32 v[68:69], v[68:69], v[72:73]
	v_pk_fma_f32 v[64:65], v[64:65], v[90:91], v[66:67] op_sel_hi:[1,0,1]
	v_pk_mul_f32 v[62:63], v[62:63], v[88:89] op_sel_hi:[1,0]
	v_pk_add_f32 v[64:65], v[64:65], v[68:69]
	v_pk_fma_f32 v[60:61], v[60:61], v[2:3], v[62:63] op_sel_hi:[1,0,1]
	s_nop 0
	v_pk_add_f32 v[86:87], v[60:61], v[64:65]
	v_and_b32_e32 v64, 64, v218
	v_add_u32_e32 v67, 64, v64
	v_xor_b32_e32 v2, 1, v218
	v_cmp_lt_i32_e32 vcc, v2, v67
	v_xor_b32_e32 v62, 2, v218
	v_xor_b32_e32 v66, 4, v218
	v_cndmask_b32_e32 v2, v218, v2, vcc
	v_lshlrev_b32_e32 v2, 2, v2
	ds_bpermute_b32 v60, v2, v84
	ds_bpermute_b32 v61, v2, v85
	v_cmp_lt_i32_e32 vcc, v62, v67
	s_add_u32 s4, s28, s22
	s_addc_u32 s5, s29, s23
	v_cndmask_b32_e32 v62, v218, v62, vcc
	v_lshlrev_b32_e32 v65, 2, v62
	s_waitcnt lgkmcnt(0)
	v_pk_add_f32 v[60:61], v[84:85], v[60:61]
	ds_bpermute_b32 v62, v65, v60
	ds_bpermute_b32 v63, v65, v61
	v_cmp_lt_i32_e32 vcc, v66, v67
	s_add_u32 s30, s4, 0x10000
	s_addc_u32 s31, s5, 0
	v_cndmask_b32_e32 v66, v218, v66, vcc
	v_lshlrev_b32_e32 v66, 2, v66
	s_waitcnt lgkmcnt(0)
	v_pk_add_f32 v[60:61], v[60:61], v[62:63]
	ds_bpermute_b32 v62, v66, v60
	ds_bpermute_b32 v63, v66, v61
	s_lshl_b32 s6, s34, 2
	s_add_u32 s6, s28, s6
	s_addc_u32 s7, s29, 0
	s_add_u32 s18, s6, 0x5200000
	s_waitcnt lgkmcnt(0)
	v_pk_add_f32 v[60:61], v[60:61], v[62:63]
	v_xor_b32_e32 v62, 8, v218
	v_cmp_lt_i32_e32 vcc, v62, v67
	v_cmp_eq_u32_e64 s[4:5], 0, v99
	s_addc_u32 s19, s7, 0
	v_cndmask_b32_e32 v62, v218, v62, vcc
	v_lshlrev_b32_e32 v67, 2, v62
	ds_bpermute_b32 v62, v67, v60
	ds_bpermute_b32 v63, v67, v61
	s_and_saveexec_b64 s[40:41], s[4:5]
	s_cbranch_execz .LBB0_330
	v_add_u32_e32 v68, s63, v102
	v_ashrrev_i32_e32 v69, 31, v68
	v_lshlrev_b64 v[72:73], 4, v[68:69]
	v_lshl_add_u64 v[68:69], s[30:31], 0, v[72:73]
	global_load_dwordx4 v[68:71], v[68:69], off
	s_mov_b32 s6, 0xf800000
	s_waitcnt lgkmcnt(0)
	v_pk_add_f32 v[60:61], v[60:61], v[62:63]
	s_waitcnt vmcnt(0)
	v_mov_b32_e32 v74, v69
	v_mov_b32_e32 v75, v70
	v_mov_b32_e32 v69, v71
	v_pk_add_f32 v[68:69], v[74:75], v[68:69]
	v_lshl_add_u32 v70, v102, 3, 0
	v_add_f32_e32 v68, v68, v69
	v_fmamk_f32 v68, v68, 0x3a800000, v215
	v_mul_f32_e32 v69, 0x4f800000, v68
	v_cmp_gt_f32_e32 vcc, s6, v68
	v_add_u32_e32 v70, 0x22c00, v70
	s_nop 0
	v_cndmask_b32_e32 v68, v68, v69, vcc
	v_sqrt_f32_e32 v69, v68
	s_nop 0
	v_add_u32_e32 v62, -1, v69
	v_add_u32_e32 v63, 1, v69
	v_fma_f32 v71, -v62, v69, v68
	v_fma_f32 v74, -v63, v69, v68
	v_cmp_ge_f32_e64 s[6:7], 0, v71
	s_nop 1
	v_cndmask_b32_e64 v62, v69, v62, s[6:7]
	v_cmp_lt_f32_e64 s[6:7], 0, v74
	s_nop 1
	v_cndmask_b32_e64 v62, v62, v63, s[6:7]
	v_mul_f32_e32 v63, 0x37800000, v62
	v_cndmask_b32_e32 v62, v62, v63, vcc
	v_cmp_class_f32_e32 vcc, v68, v216
	s_nop 1
	v_cndmask_b32_e32 v68, v62, v68, vcc
	v_div_scale_f32 v69, s[6:7], v68, v68, 1.0
	v_rcp_f32_e32 v71, v69
	v_lshl_add_u64 v[62:63], s[18:19], 0, v[72:73]
	v_div_scale_f32 v72, vcc, 1.0, v68, 1.0
	v_fma_f32 v73, -v69, v71, 1.0
	v_fmac_f32_e32 v71, v73, v71
	v_mul_f32_e32 v73, v72, v71
	v_fma_f32 v74, -v69, v73, v72
	v_fmac_f32_e32 v73, v74, v71
	v_fma_f32 v69, -v69, v73, v72
	v_div_fmas_f32 v69, v69, v71, v73
	v_div_fixup_f32 v68, v69, v68, 1.0
	v_pk_mul_f32 v[60:61], v[60:61], v[68:69] op_sel_hi:[1,0]
	ds_write_b64 v70, v[60:61]
	global_store_dwordx2 v[62:63], v[60:61], off

.LBB0_361:
	ds_read_b128 v[74:77], v73
	ds_read_b128 v[78:81], v72
	s_add_i32 s1, s1, 16
	v_add_u32_e32 v73, 32, v73
	s_cmp_lt_u32 s1, s13
	v_add_u32_e32 v72, 32, v72
	s_waitcnt lgkmcnt(0)
	v_mfma_f32_32x32x16_bf16 v[4:19], v[74:77], v[78:81], v[4:19]
	s_cbranch_scc1 .LBB0_361
	s_load_dwordx2 s[4:5], s[94:95], 0x28
	s_waitcnt vmcnt(21)
	v_lshlrev_b32_e32 v74, 16, v66
	v_lshlrev_b32_e32 v66, 16, v2
	v_lshlrev_b32_e32 v2, 1, v40
	s_waitcnt vmcnt(19)
	v_lshlrev_b32_e32 v72, 16, v68
	v_lshlrev_b32_e32 v68, 16, v41
	v_lshl_add_u64 v[40:41], s[18:19], 0, v[2:3]
	s_mov_b64 s[6:7], 0xb300000
	s_or_b32 s34, s34, s11
	v_lshl_add_u64 v[40:41], v[40:41], 0, s[6:7]
	s_lshl_b64 s[6:7], s[34:35], 2
	v_lshlrev_b32_e32 v73, 16, v67
	v_lshlrev_b32_e32 v67, 16, v39
	s_waitcnt lgkmcnt(0)
	s_add_u32 s6, s4, s6
	v_ashrrev_i32_e32 v39, 31, v38
	v_lshlrev_b32_e32 v83, 16, v43
	v_lshlrev_b32_e32 v84, 16, v42
	s_addc_u32 s7, s5, s7
	v_lshlrev_b64 v[42:43], 2, v[38:39]
	v_lshlrev_b32_e32 v76, 16, v47
	v_lshlrev_b32_e32 v77, 16, v46
	v_lshl_add_u64 v[46:47], s[6:7], 0, v[42:43]
	global_load_dwordx4 v[78:81], v[46:47], off
	s_lshl_b32 s34, s28, 1
	v_lshlrev_b32_e32 v75, 16, v65
	v_lshlrev_b32_e32 v65, 16, v45
	v_lshlrev_b32_e32 v82, 16, v44
	v_lshl_add_u64 v[44:45], v[40:41], 0, s[34:35]
	v_lshlrev_b64 v[48:49], 11, v[48:49]
	v_lshl_add_u64 v[48:49], v[44:45], 0, v[48:49]
	v_add_u32_e32 v39, 8, v38
	s_waitcnt vmcnt(19)
	v_lshlrev_b32_e32 v71, 16, v71
	s_waitcnt vmcnt(18)
	v_lshlrev_b32_e32 v70, 16, v70
	s_waitcnt vmcnt(17)
	v_lshlrev_b32_e32 v69, 16, v69
	s_or_b32 s34, s0, s11
	s_lshl_b64 s[0:1], s[34:35], 2
	s_add_u32 s0, s4, s0
	s_addc_u32 s1, s5, s1
	v_lshl_add_u64 v[142:143], s[0:1], 0, v[42:43]
	global_load_dwordx4 v[114:117], v[46:47], off offset:32
	global_load_dwordx4 v[118:121], v[46:47], off offset:64
	global_load_dwordx4 v[122:125], v[46:47], off offset:96
	global_load_dwordx4 v[126:129], v[142:143], off
	global_load_dwordx4 v[130:133], v[142:143], off offset:32
	global_load_dwordx4 v[134:137], v[142:143], off offset:64
	global_load_dwordx4 v[138:141], v[142:143], off offset:96
	s_waitcnt vmcnt(23)
	v_lshlrev_b32_e32 v64, 16, v64
	s_lshl_b32 s34, s26, 1
	v_lshlrev_b64 v[36:37], 11, v[36:37]
	s_waitcnt vmcnt(22)
	v_lshlrev_b32_e32 v63, 16, v63
	s_waitcnt vmcnt(21)
	v_lshlrev_b32_e32 v62, 16, v62
	s_waitcnt vmcnt(20)
	v_lshlrev_b32_e32 v61, 16, v61
	s_waitcnt vmcnt(19)
	v_lshlrev_b32_e32 v60, 16, v60
	s_waitcnt vmcnt(18)
	v_lshlrev_b32_e32 v59, 16, v59
	s_waitcnt vmcnt(17)
	v_lshlrev_b32_e32 v58, 16, v58
	s_waitcnt vmcnt(16)
	v_lshlrev_b32_e32 v57, 16, v57
	s_waitcnt vmcnt(15)
	v_lshlrev_b32_e32 v56, 16, v56
	s_waitcnt vmcnt(14)
	v_lshlrev_b32_e32 v55, 16, v55
	s_waitcnt vmcnt(13)
	v_lshlrev_b32_e32 v54, 16, v54
	s_waitcnt vmcnt(12)
	v_lshlrev_b32_e32 v53, 16, v53
	s_waitcnt vmcnt(11)
	v_lshlrev_b32_e32 v52, 16, v52
	s_waitcnt vmcnt(10)
	v_lshlrev_b32_e32 v51, 16, v51
	s_waitcnt vmcnt(9)
	v_lshlrev_b32_e32 v50, 16, v50
	s_waitcnt vmcnt(8)
	v_lshlrev_b32_e32 v1, 16, v1
	s_waitcnt vmcnt(0)
	v_add_f32_e32 v2, v20, v78
	v_mul_f32_e32 v2, v2, v66
	v_bfe_u32 v20, v2, 16, 1
	v_add3_u32 v2, v2, v20, s20
	global_store_short_d16_hi v[48:49], v2, off
	v_add_f32_e32 v2, v21, v79
	v_mul_f32_e32 v2, v2, v67
	v_or_b32_e32 v66, 1, v38
	v_bfe_u32 v20, v2, 16, 1
	v_add3_u32 v2, v2, v20, s20
	v_add_u32_e32 v20, s27, v66
	v_ashrrev_i32_e32 v21, 31, v20
	v_lshlrev_b64 v[20:21], 11, v[20:21]
	v_lshl_add_u64 v[20:21], v[44:45], 0, v[20:21]
	global_store_short_d16_hi v[20:21], v2, off
	v_add_f32_e32 v2, v22, v80
	v_mul_f32_e32 v2, v2, v68
	v_or_b32_e32 v67, 2, v38
	v_bfe_u32 v20, v2, 16, 1
	v_add3_u32 v2, v2, v20, s20
	v_add_u32_e32 v20, s27, v67
	v_ashrrev_i32_e32 v21, 31, v20
	v_lshlrev_b64 v[20:21], 11, v[20:21]
	v_lshl_add_u64 v[20:21], v[44:45], 0, v[20:21]
	global_store_short_d16_hi v[20:21], v2, off
	v_add_f32_e32 v2, v23, v81
	v_mul_f32_e32 v2, v2, v84
	v_or_b32_e32 v68, 3, v38
	v_bfe_u32 v20, v2, 16, 1
	v_add3_u32 v2, v2, v20, s20
	v_add_u32_e32 v20, s27, v68
	v_ashrrev_i32_e32 v21, 31, v20
	v_lshlrev_b64 v[20:21], 11, v[20:21]
	v_lshl_add_u64 v[20:21], v[44:45], 0, v[20:21]
	global_store_short_d16_hi v[20:21], v2, off
	v_add_u32_e32 v48, s27, v39
	v_ashrrev_i32_e32 v49, 31, v48
	v_lshlrev_b64 v[48:49], 11, v[48:49]
	v_lshl_add_u64 v[48:49], v[44:45], 0, v[48:49]
	v_mov_b64_e32 v[20:21], v[114:115]
	v_mov_b64_e32 v[22:23], v[116:117]
	v_add_f32_e32 v2, v24, v20
	v_mul_f32_e32 v2, v2, v83
	v_bfe_u32 v20, v2, 16, 1
	v_add3_u32 v2, v2, v20, s20
	global_store_short_d16_hi v[48:49], v2, off
	v_add_f32_e32 v2, v25, v21
	v_mul_f32_e32 v2, v2, v82
	v_add_u32_e32 v48, 9, v38
	v_bfe_u32 v20, v2, 16, 1
	v_add3_u32 v2, v2, v20, s20
	v_add_u32_e32 v20, s27, v48
	v_ashrrev_i32_e32 v21, 31, v20
	v_lshlrev_b64 v[20:21], 11, v[20:21]
	v_lshl_add_u64 v[20:21], v[44:45], 0, v[20:21]
	global_store_short_d16_hi v[20:21], v2, off
	v_add_f32_e32 v2, v26, v22
	v_mul_f32_e32 v2, v2, v65
	v_add_u32_e32 v49, 10, v38
	v_bfe_u32 v20, v2, 16, 1
	v_add3_u32 v2, v2, v20, s20
	v_add_u32_e32 v20, s27, v49
	v_ashrrev_i32_e32 v21, 31, v20
	v_lshlrev_b64 v[20:21], 11, v[20:21]
	v_lshl_add_u64 v[20:21], v[44:45], 0, v[20:21]
	global_store_short_d16_hi v[20:21], v2, off
	v_add_f32_e32 v2, v27, v23
	v_mul_f32_e32 v2, v2, v77
	v_add_u32_e32 v65, 11, v38
	v_bfe_u32 v20, v2, 16, 1
	v_add3_u32 v2, v2, v20, s20
	v_add_u32_e32 v20, s27, v65
	v_ashrrev_i32_e32 v21, 31, v20
	v_lshlrev_b64 v[20:21], 11, v[20:21]
	v_lshl_add_u64 v[20:21], v[44:45], 0, v[20:21]
	global_store_short_d16_hi v[20:21], v2, off
	v_add_u32_e32 v24, 16, v38
	v_add_u32_e32 v26, s27, v24
	v_ashrrev_i32_e32 v27, 31, v26
	v_lshlrev_b64 v[26:27], 11, v[26:27]
	v_lshl_add_u64 v[26:27], v[44:45], 0, v[26:27]
	v_mov_b64_e32 v[20:21], v[118:119]
	v_mov_b64_e32 v[22:23], v[120:121]
	v_add_f32_e32 v2, v28, v20
	v_mul_f32_e32 v2, v2, v76
	v_bfe_u32 v20, v2, 16, 1
	v_add3_u32 v2, v2, v20, s20
	global_store_short_d16_hi v[26:27], v2, off
	v_add_f32_e32 v2, v29, v21
	v_mul_f32_e32 v2, v2, v75
	v_add_u32_e32 v28, 17, v38
	v_bfe_u32 v20, v2, 16, 1
	v_add3_u32 v2, v2, v20, s20
	v_add_u32_e32 v20, s27, v28
	v_ashrrev_i32_e32 v21, 31, v20
	v_lshlrev_b64 v[20:21], 11, v[20:21]
	v_lshl_add_u64 v[20:21], v[44:45], 0, v[20:21]
	global_store_short_d16_hi v[20:21], v2, off
	v_add_f32_e32 v2, v30, v22
	v_mul_f32_e32 v2, v2, v74
	v_add_u32_e32 v29, 18, v38
	v_bfe_u32 v20, v2, 16, 1
	v_add3_u32 v2, v2, v20, s20
	v_add_u32_e32 v20, s27, v29
	v_ashrrev_i32_e32 v21, 31, v20
	v_lshlrev_b64 v[20:21], 11, v[20:21]
	v_lshl_add_u64 v[20:21], v[44:45], 0, v[20:21]
	global_store_short_d16_hi v[20:21], v2, off
	v_add_f32_e32 v2, v31, v23
	v_mul_f32_e32 v2, v2, v73
	v_add_u32_e32 v30, 19, v38
	v_bfe_u32 v20, v2, 16, 1
	v_add3_u32 v2, v2, v20, s20
	v_add_u32_e32 v20, s27, v30
	v_ashrrev_i32_e32 v21, 31, v20
	v_lshlrev_b64 v[20:21], 11, v[20:21]
	v_lshl_add_u64 v[20:21], v[44:45], 0, v[20:21]
	global_store_short_d16_hi v[20:21], v2, off
	v_add_u32_e32 v2, 24, v38
	v_add_u32_e32 v26, s27, v2
	v_ashrrev_i32_e32 v27, 31, v26
	v_lshlrev_b64 v[26:27], 11, v[26:27]
	v_lshl_add_u64 v[26:27], v[44:45], 0, v[26:27]
	v_mov_b64_e32 v[20:21], v[122:123]
	v_mov_b64_e32 v[22:23], v[124:125]
	v_add_f32_e32 v20, v32, v20
	v_mul_f32_e32 v20, v20, v72
	v_bfe_u32 v25, v20, 16, 1
	v_add3_u32 v20, v20, v25, s20
	global_store_short_d16_hi v[26:27], v20, off
	v_add_f32_e32 v20, v33, v21
	v_mul_f32_e32 v20, v20, v71
	v_add_u32_e32 v27, 25, v38
	v_bfe_u32 v21, v20, 16, 1
	v_add3_u32 v25, v20, v21, s20
	v_add_u32_e32 v20, s27, v27
	v_ashrrev_i32_e32 v21, 31, v20
	v_lshlrev_b64 v[20:21], 11, v[20:21]
	v_lshl_add_u64 v[20:21], v[44:45], 0, v[20:21]
	global_store_short_d16_hi v[20:21], v25, off
	v_add_f32_e32 v20, v34, v22
	v_mul_f32_e32 v20, v20, v70
	v_add_u32_e32 v26, 26, v38
	v_bfe_u32 v21, v20, 16, 1
	v_add3_u32 v22, v20, v21, s20
	v_add_u32_e32 v20, s27, v26
	v_ashrrev_i32_e32 v21, 31, v20
	v_lshlrev_b64 v[20:21], 11, v[20:21]
	v_lshl_add_u64 v[20:21], v[44:45], 0, v[20:21]
	global_store_short_d16_hi v[20:21], v22, off
	v_add_f32_e32 v20, v35, v23
	v_mul_f32_e32 v20, v20, v69
	v_add_u32_e32 v25, 27, v38
	v_bfe_u32 v21, v20, 16, 1
	v_add3_u32 v22, v20, v21, s20
	v_add_u32_e32 v20, s27, v25
	v_ashrrev_i32_e32 v21, 31, v20
	v_lshlrev_b64 v[20:21], 11, v[20:21]
	v_lshl_add_u64 v[20:21], v[44:45], 0, v[20:21]
	global_store_short_d16_hi v[20:21], v22, off
	v_lshl_add_u64 v[22:23], s[0:1], 0, v[42:43]
	v_lshl_add_u64 v[20:21], v[40:41], 0, s[34:35]
	v_lshl_add_u64 v[36:37], v[20:21], 0, v[36:37]
	v_readlane_b32 s26, v255, 18
	v_readlane_b32 s27, v255, 19
	v_mov_b64_e32 v[32:33], v[126:127]
	v_mov_b64_e32 v[34:35], v[128:129]
	v_add_f32_e32 v4, v4, v32
	v_mul_f32_e32 v4, v4, v64
	v_bfe_u32 v31, v4, 16, 1
	v_add3_u32 v4, v4, v31, s20
	global_store_short_d16_hi v[36:37], v4, off
	v_add_f32_e32 v4, v5, v33
	v_mul_f32_e32 v4, v4, v63
	v_bfe_u32 v5, v4, 16, 1
	v_add3_u32 v31, v4, v5, s20
	v_add_u32_e32 v4, s15, v66
	v_ashrrev_i32_e32 v5, 31, v4
	v_lshlrev_b64 v[4:5], 11, v[4:5]
	v_lshl_add_u64 v[4:5], v[20:21], 0, v[4:5]
	global_store_short_d16_hi v[4:5], v31, off
	v_add_f32_e32 v4, v6, v34
	v_mul_f32_e32 v4, v4, v62
	v_bfe_u32 v5, v4, 16, 1
	v_add3_u32 v6, v4, v5, s20
	v_add_u32_e32 v4, s15, v67
	v_ashrrev_i32_e32 v5, 31, v4
	v_lshlrev_b64 v[4:5], 11, v[4:5]
	v_lshl_add_u64 v[4:5], v[20:21], 0, v[4:5]
	global_store_short_d16_hi v[4:5], v6, off
	v_add_f32_e32 v4, v7, v35
	v_mul_f32_e32 v4, v4, v61
	v_bfe_u32 v5, v4, 16, 1
	v_add3_u32 v6, v4, v5, s20
	v_add_u32_e32 v4, s15, v68
	v_ashrrev_i32_e32 v5, 31, v4
	v_lshlrev_b64 v[4:5], 11, v[4:5]
	v_lshl_add_u64 v[4:5], v[20:21], 0, v[4:5]
	global_store_short_d16_hi v[4:5], v6, off
	v_add_u32_e32 v32, s15, v39
	v_ashrrev_i32_e32 v33, 31, v32
	v_lshlrev_b64 v[32:33], 11, v[32:33]
	v_lshl_add_u64 v[32:33], v[20:21], 0, v[32:33]
	v_mov_b64_e32 v[4:5], v[130:131]
	v_mov_b64_e32 v[6:7], v[132:133]
	v_add_f32_e32 v4, v8, v4
	v_mul_f32_e32 v4, v4, v60
	v_bfe_u32 v8, v4, 16, 1
	v_add3_u32 v4, v4, v8, s20
	global_store_short_d16_hi v[32:33], v4, off
	v_add_f32_e32 v4, v9, v5
	v_mul_f32_e32 v4, v4, v59
	v_bfe_u32 v5, v4, 16, 1
	v_add3_u32 v8, v4, v5, s20
	v_add_u32_e32 v4, s15, v48
	v_ashrrev_i32_e32 v5, 31, v4
	v_lshlrev_b64 v[4:5], 11, v[4:5]
	v_lshl_add_u64 v[4:5], v[20:21], 0, v[4:5]
	global_store_short_d16_hi v[4:5], v8, off
	v_add_f32_e32 v4, v10, v6
	v_mul_f32_e32 v4, v4, v58
	v_bfe_u32 v5, v4, 16, 1
	v_add3_u32 v6, v4, v5, s20
	v_add_u32_e32 v4, s15, v49
	v_ashrrev_i32_e32 v5, 31, v4
	v_lshlrev_b64 v[4:5], 11, v[4:5]
	v_lshl_add_u64 v[4:5], v[20:21], 0, v[4:5]
	global_store_short_d16_hi v[4:5], v6, off
	v_add_f32_e32 v4, v11, v7
	v_mul_f32_e32 v4, v4, v57
	v_bfe_u32 v5, v4, 16, 1
	v_add3_u32 v6, v4, v5, s20
	v_add_u32_e32 v4, s15, v65
	v_ashrrev_i32_e32 v5, 31, v4
	v_lshlrev_b64 v[4:5], 11, v[4:5]
	v_lshl_add_u64 v[4:5], v[20:21], 0, v[4:5]
	global_store_short_d16_hi v[4:5], v6, off
	v_mov_b64_e32 v[4:5], v[134:135]
	v_mov_b64_e32 v[6:7], v[136:137]
	v_add_f32_e32 v4, v12, v4
	v_mul_f32_e32 v4, v4, v56
	v_bfe_u32 v8, v4, 16, 1
	v_add3_u32 v4, v4, v8, s20
	v_add_u32_e32 v8, s15, v24
	v_ashrrev_i32_e32 v9, 31, v8
	v_lshlrev_b64 v[8:9], 11, v[8:9]
	v_lshl_add_u64 v[8:9], v[20:21], 0, v[8:9]
	global_store_short_d16_hi v[8:9], v4, off
	v_add_f32_e32 v4, v13, v5
	v_mul_f32_e32 v4, v4, v55
	v_bfe_u32 v5, v4, 16, 1
	v_add3_u32 v8, v4, v5, s20
	v_add_u32_e32 v4, s15, v28
	v_ashrrev_i32_e32 v5, 31, v4
	v_lshlrev_b64 v[4:5], 11, v[4:5]
	v_lshl_add_u64 v[4:5], v[20:21], 0, v[4:5]
	global_store_short_d16_hi v[4:5], v8, off
	v_add_f32_e32 v4, v14, v6
	v_mul_f32_e32 v4, v4, v54
	v_bfe_u32 v5, v4, 16, 1
	v_add3_u32 v6, v4, v5, s20
	v_add_u32_e32 v4, s15, v29
	v_ashrrev_i32_e32 v5, 31, v4
	v_lshlrev_b64 v[4:5], 11, v[4:5]
	v_lshl_add_u64 v[4:5], v[20:21], 0, v[4:5]
	global_store_short_d16_hi v[4:5], v6, off
	v_add_f32_e32 v4, v15, v7
	v_mul_f32_e32 v4, v4, v53
	v_bfe_u32 v5, v4, 16, 1
	v_add3_u32 v6, v4, v5, s20
	v_add_u32_e32 v4, s15, v30
	v_ashrrev_i32_e32 v5, 31, v4
	v_lshlrev_b64 v[4:5], 11, v[4:5]
	v_lshl_add_u64 v[4:5], v[20:21], 0, v[4:5]
	global_store_short_d16_hi v[4:5], v6, off
	v_mov_b64_e32 v[4:5], v[138:139]
	v_mov_b64_e32 v[6:7], v[140:141]
	v_add_f32_e32 v4, v16, v4
	v_mul_f32_e32 v4, v4, v52
	v_bfe_u32 v8, v4, 16, 1
	v_add3_u32 v4, v4, v8, s20
	v_add_u32_e32 v8, s15, v2
	v_ashrrev_i32_e32 v9, 31, v8
	v_lshlrev_b64 v[8:9], 11, v[8:9]
	v_add_f32_e32 v2, v17, v5
	v_lshl_add_u64 v[8:9], v[20:21], 0, v[8:9]
	v_mul_f32_e32 v2, v2, v51
	global_store_short_d16_hi v[8:9], v4, off
	v_bfe_u32 v4, v2, 16, 1
	v_add3_u32 v2, v2, v4, s20
	v_add_u32_e32 v4, s15, v27
	v_ashrrev_i32_e32 v5, 31, v4
	v_lshlrev_b64 v[4:5], 11, v[4:5]
	v_lshl_add_u64 v[4:5], v[20:21], 0, v[4:5]
	global_store_short_d16_hi v[4:5], v2, off
	v_add_f32_e32 v2, v18, v6
	v_mul_f32_e32 v2, v2, v50
	v_bfe_u32 v4, v2, 16, 1
	v_add3_u32 v2, v2, v4, s20
	v_add_u32_e32 v4, s15, v26
	v_ashrrev_i32_e32 v5, 31, v4
	v_lshlrev_b64 v[4:5], 11, v[4:5]
	v_lshl_add_u64 v[4:5], v[20:21], 0, v[4:5]
	global_store_short_d16_hi v[4:5], v2, off
	v_add_f32_e32 v2, v19, v7
	v_add_u32_e32 v4, s15, v25
	v_mul_f32_e32 v1, v2, v1
	v_ashrrev_i32_e32 v5, 31, v4
	v_bfe_u32 v2, v1, 16, 1
	v_lshlrev_b64 v[4:5], 11, v[4:5]
	v_add3_u32 v1, v1, v2, s20
	v_lshl_add_u64 v[4:5], v[20:21], 0, v[4:5]
	global_store_short_d16_hi v[4:5], v1, off
	s_barrier
	s_branch .LBB0_352

.LBB0_683:
	s_not_b32 s8, s56
	v_ashrrev_i32_e32 v8, 3, v2
	s_lshl_b32 s8, s8, 1
	v_ashrrev_i32_e32 v9, 31, v8
	v_ldexp_f32 v6, 1.0, s8
	v_lshl_add_u64 v[10:11], s[4:5], 0, v[8:9]
	v_mov_b64_e32 v[12:13], s[6:7]
	s_movk_i32 s8, 0x1200
	v_ashrrev_i32_e32 v34, 4, v2
	v_mad_u64_u32 v[12:13], s[6:7], v10, s8, v[12:13]
	v_add_u32_e32 v10, s55, v34
	v_mad_i32_i24 v13, v11, s8, v13
	v_ashrrev_i32_e32 v11, 31, v10
	v_lshlrev_b64 v[10:11], 15, v[10:11]
	v_lshlrev_b32_e32 v2, 4, v2
	v_lshlrev_b32_e32 v166, 2, v25
	v_lshl_add_u64 v[10:11], s[26:27], 0, v[10:11]
	v_and_b32_e32 v14, 0x70, v2
	v_or_b32_e32 v9, 1, v166
	s_movk_i32 s6, 0x90
	v_mul_f32_e32 v7, 0x3fb8aa3b, v160
	v_or_b32_e32 v35, 3, v166
	v_or_b32_e32 v52, 2, v166
	v_add_u32_e32 v164, 8, v166
	v_add_u32_e32 v53, 9, v166
	v_add_u32_e32 v54, 10, v166
	v_add_u32_e32 v55, 11, v166
	v_add_u32_e32 v162, 16, v166
	v_add_u32_e32 v56, 17, v166
	v_add_u32_e32 v57, 18, v166
	v_add_u32_e32 v58, 19, v166
	v_add_u32_e32 v160, 24, v166
	v_add_u32_e32 v59, 25, v166
	v_add_u32_e32 v60, 26, v166
	v_add_u32_e32 v61, 27, v166
	v_cvt_f32_i32_e32 v19, v9
	v_mad_u64_u32 v[176:177], s[6:7], v8, s6, v[14:15]
	v_lshl_add_u64 v[8:9], s[4:5], 1, v[10:11]
	v_and_b32_e32 v2, 0xf0, v2
	v_cvt_f32_i32_e32 v17, v35
	v_cvt_f32_i32_e32 v16, v52
	v_cvt_f32_i32_e32 v18, v166
	v_cvt_f32_i32_e32 v21, v53
	v_cvt_f32_i32_e32 v20, v164
	v_cvt_f32_i32_e32 v23, v55
	v_cvt_f32_i32_e32 v22, v54
	v_cvt_f32_i32_e32 v27, v56
	v_cvt_f32_i32_e32 v26, v162
	v_cvt_f32_i32_e32 v29, v58
	v_cvt_f32_i32_e32 v31, v59
	v_cvt_f32_i32_e32 v33, v61
	v_cvt_f32_i32_e32 v32, v60
	v_cvt_f32_i32_e32 v30, v160
	v_cvt_f32_i32_e32 v28, v57
	v_lshl_add_u64 v[8:9], v[8:9], 0, v[2:3]
	s_mov_b64 s[4:5], 0x6300000
	s_lshl_b32 s18, s55, 1
	s_mov_b32 s19, s35
	v_lshl_add_u64 v[178:179], v[8:9], 0, s[4:5]
	v_lshl_add_u64 v[8:9], v[12:13], 0, s[18:19]
	v_mov_b32_e32 v15, v3
	v_lshl_add_u64 v[8:9], v[8:9], 0, v[14:15]
	s_mov_b64 s[4:5], 0x1000
	v_mul_f32_e32 v6, 0x3fb8aa3b, v6
	v_lshl_add_u64 v[180:181], v[8:9], 0, s[4:5]
	v_and_b32_e32 v8, 0xffff0000, v100
	v_pk_mul_f32 v[38:39], v[6:7], v[16:17] op_sel_hi:[0,1]
	v_pk_mul_f32 v[50:51], v[6:7], v[32:33] op_sel_hi:[0,1]
	v_pk_mul_f32 v[48:49], v[6:7], v[30:31] op_sel_hi:[0,1]
	v_pk_mul_f32 v[46:47], v[6:7], v[28:29] op_sel_hi:[0,1]
	v_pk_mul_f32 v[44:45], v[6:7], v[26:27] op_sel_hi:[0,1]
	v_pk_mul_f32 v[42:43], v[6:7], v[22:23] op_sel_hi:[0,1]
	v_pk_mul_f32 v[40:41], v[6:7], v[20:21] op_sel_hi:[0,1]
	v_pk_mul_f32 v[36:37], v[6:7], v[18:19] op_sel_hi:[0,1]
	v_exp_f32_e32 v165, v7
	v_lshlrev_b32_e32 v7, 16, v100
	v_mul_f32_e32 v8, v8, v8
	v_fmac_f32_e32 v8, v7, v7
	v_lshlrev_b32_e32 v7, 16, v101
	v_fmac_f32_e32 v8, v7, v7
	v_and_b32_e32 v7, 0xffff0000, v101
	v_fmac_f32_e32 v8, v7, v7
	v_lshlrev_b32_e32 v7, 16, v102
	v_fmac_f32_e32 v8, v7, v7
	v_and_b32_e32 v7, 0xffff0000, v102
	v_fmac_f32_e32 v8, v7, v7
	v_lshlrev_b32_e32 v7, 16, v103
	v_fmac_f32_e32 v8, v7, v7
	v_and_b32_e32 v7, 0xffff0000, v103
	v_fmac_f32_e32 v8, v7, v7
	v_lshlrev_b32_e32 v7, 16, v104
	v_fmac_f32_e32 v8, v7, v7
	v_and_b32_e32 v7, 0xffff0000, v104
	v_fmac_f32_e32 v8, v7, v7
	v_lshlrev_b32_e32 v7, 16, v105
	v_fmac_f32_e32 v8, v7, v7
	v_and_b32_e32 v7, 0xffff0000, v105
	v_fmac_f32_e32 v8, v7, v7
	v_lshlrev_b32_e32 v7, 16, v106
	v_fmac_f32_e32 v8, v7, v7
	v_and_b32_e32 v7, 0xffff0000, v106
	v_fmac_f32_e32 v8, v7, v7
	v_lshlrev_b32_e32 v7, 16, v107
	v_fmac_f32_e32 v8, v7, v7
	v_and_b32_e32 v7, 0xffff0000, v107
	v_fmac_f32_e32 v8, v7, v7
	v_mov_b32_e32 v7, v8
	s_and_b32 s6, s11, 7
	s_nop 0
	v_permlane32_swap_b32_e32 v8, v7
	s_lshl_b32 s28, s6, 2
	s_xor_b32 s19, s54, 15
	v_add_f32_e32 v7, v8, v7
	s_mov_b32 s6, 0xf800000
	v_mul_f32_e32 v8, 0x4f800000, v7
	v_cmp_gt_f32_e32 vcc, s6, v7
	s_lshl_b32 s34, s19, 8
	s_mov_b32 s4, 0x48000
	v_cndmask_b32_e32 v7, v7, v8, vcc
	v_lshl_add_u64 v[8:9], v[178:179], 0, s[34:35]
	s_mul_i32 s34, s19, 0x90000
	v_lshl_add_u64 v[10:11], v[180:181], 0, s[34:35]
	global_load_dwordx4 v[116:119], v[10:11], off
	global_load_dwordx4 v[120:123], v[8:9], off
	v_add_co_u32_e64 v10, s[4:5], s4, v10
	v_sqrt_f32_e32 v12, v7
	s_nop 0
	v_addc_co_u32_e64 v11, s[4:5], 0, v11, s[4:5]
	s_mov_b32 s4, 0x100000
	s_nop 0
	v_add_co_u32_e64 v8, s[4:5], s4, v8
	global_load_dwordx4 v[124:127], v[10:11], off
	s_nop 0
	v_addc_co_u32_e64 v9, s[4:5], 0, v9, s[4:5]
	global_load_dwordx4 v[128:131], v[8:9], off
	v_mul_f32_e32 v167, 0x42000000, v6
	v_mul_f32_e32 v177, 0x41f80000, v6
	v_add_u32_e32 v6, -1, v12
	v_fma_f32 v8, -v6, v12, v7
	v_cmp_ge_f32_e64 s[4:5], 0, v8
	v_add_u32_e32 v8, 1, v12
	v_fma_f32 v9, -v8, v12, v7
	v_cndmask_b32_e64 v6, v12, v6, s[4:5]
	v_cmp_lt_f32_e64 s[4:5], 0, v9
	v_and_b32_e32 v9, 0xffff0000, v108
	v_mul_f32_e32 v9, v9, v9
	v_cndmask_b32_e64 v6, v6, v8, s[4:5]
	v_mul_f32_e32 v8, 0x37800000, v6
	v_cndmask_b32_e32 v6, v6, v8, vcc
	v_lshlrev_b32_e32 v8, 16, v108
	v_fmac_f32_e32 v9, v8, v8
	v_lshlrev_b32_e32 v8, 16, v109
	v_fmac_f32_e32 v9, v8, v8
	v_and_b32_e32 v8, 0xffff0000, v109
	v_fmac_f32_e32 v9, v8, v8
	v_lshlrev_b32_e32 v8, 16, v110
	v_fmac_f32_e32 v9, v8, v8
	v_and_b32_e32 v8, 0xffff0000, v110
	v_fmac_f32_e32 v9, v8, v8
	v_lshlrev_b32_e32 v8, 16, v111
	v_fmac_f32_e32 v9, v8, v8
	v_and_b32_e32 v8, 0xffff0000, v111
	v_fmac_f32_e32 v9, v8, v8
	v_lshlrev_b32_e32 v8, 16, v112
	v_fmac_f32_e32 v9, v8, v8
	v_and_b32_e32 v8, 0xffff0000, v112
	v_fmac_f32_e32 v9, v8, v8
	v_lshlrev_b32_e32 v8, 16, v113
	v_fmac_f32_e32 v9, v8, v8
	v_and_b32_e32 v8, 0xffff0000, v113
	v_fmac_f32_e32 v9, v8, v8
	v_lshlrev_b32_e32 v8, 16, v114
	v_fmac_f32_e32 v9, v8, v8
	v_and_b32_e32 v8, 0xffff0000, v114
	v_fmac_f32_e32 v9, v8, v8
	v_lshlrev_b32_e32 v8, 16, v115
	v_fmac_f32_e32 v9, v8, v8
	v_and_b32_e32 v8, 0xffff0000, v115
	v_fmac_f32_e32 v9, v8, v8
	v_mov_b32_e32 v8, v9
	s_nop 1
	v_permlane32_swap_b32_e32 v9, v8
	v_add_f32_e32 v8, v9, v8
	v_mul_f32_e32 v9, 0x4f800000, v8
	v_cmp_gt_f32_e32 vcc, s6, v8
	v_cmp_class_f32_e64 s[4:5], v7, v216
	v_mul_f32_e32 v5, 0x40b6d45c, v5
	v_cndmask_b32_e32 v8, v8, v9, vcc
	v_sqrt_f32_e32 v9, v8
	v_cndmask_b32_e64 v6, v6, v7, s[4:5]
	v_fma_f32 v184, v5, v6, v177
	v_readlane_b32 s29, v255, 6
	v_add_u32_e32 v6, -1, v9
	v_fma_f32 v7, -v6, v9, v8
	v_cmp_ge_f32_e64 s[4:5], 0, v7
	v_add_u32_e32 v7, 1, v9
	v_mov_b32_e32 v16, v3
	v_cndmask_b32_e64 v6, v9, v6, s[4:5]
	v_fma_f32 v9, -v7, v9, v8
	v_cmp_lt_f32_e64 s[4:5], 0, v9
	v_mov_b32_e32 v17, v3
	v_cmp_lt_i32_e64 s[6:7], v166, v24
	v_cndmask_b32_e64 v6, v6, v7, s[4:5]
	v_mul_f32_e32 v7, 0x37800000, v6
	s_movk_i32 s4, 0x108
	v_cndmask_b32_e32 v6, v6, v7, vcc
	v_cmp_class_f32_e32 vcc, v8, v216
	v_mad_u64_u32 v[182:183], s[4:5], v34, s4, v[2:3]
	s_nop 0
	v_cndmask_b32_e32 v6, v6, v8, vcc
	v_add_u32_e32 v2, 0, v182
	v_fmac_f32_e32 v177, v5, v6
	v_add_u32_e32 v5, 0, v176
	v_add_u32_e32 v6, 0x4800, v2
	s_waitcnt vmcnt(3)
	ds_write_b128 v5, v[116:119]
	s_waitcnt vmcnt(2)
	ds_write2_b64 v6, v[120:121], v[122:123] offset1:1
	s_waitcnt vmcnt(1)
	ds_write_b128 v5, v[124:127] offset:9216
	v_add_u32_e32 v2, 0x6900, v2
	v_mul_u32_u24_e32 v6, 0x108, v24
	s_waitcnt vmcnt(0)
	ds_write2_b64 v2, v[128:129], v[130:131] offset1:1
	v_mul_u32_u24_e32 v2, 0x90, v24
	v_lshlrev_b32_e32 v5, 4, v25
	v_add3_u32 v185, v6, v4, s29
	v_readlane_b32 s29, v254, 54
	v_cmp_gt_i32_e64 s[4:5], v166, v24
	v_cmp_gt_i32_e64 s[8:9], v52, v24
	v_cmp_gt_i32_e64 s[40:41], v35, v24
	v_cmp_gt_i32_e64 s[42:43], v164, v24
	v_cmp_gt_i32_e64 s[44:45], v53, v24
	v_cmp_gt_i32_e64 s[46:47], v54, v24
	v_cmp_gt_i32_e64 s[48:49], v55, v24
	v_cmp_gt_i32_e64 s[50:51], v162, v24
	v_cmp_gt_i32_e64 s[52:53], v56, v24
	v_cmp_gt_i32_e64 s[54:55], v57, v24
	v_cmp_gt_i32_e64 s[56:57], v58, v24
	v_cmp_gt_i32_e64 s[58:59], v160, v24
	v_cmp_gt_i32_e64 s[60:61], v59, v24
	v_cmp_gt_i32_e64 s[62:63], v60, v24
	v_cmp_gt_i32_e64 s[64:65], v61, v24
	v_add3_u32 v186, v2, v5, s29
	s_lshl_b32 s29, s19, 2
	v_readlane_b32 s31, v254, 59
	v_mov_b32_e32 v2, v3
	v_mov_b32_e32 v4, v3
	v_mov_b32_e32 v5, v3
	v_mov_b32_e32 v6, v3
	v_mov_b32_e32 v7, v3
	v_mov_b32_e32 v8, v3
	v_mov_b32_e32 v9, v3
	v_mov_b32_e32 v10, v3
	v_mov_b32_e32 v11, v3
	v_mov_b32_e32 v12, v3
	v_mov_b32_e32 v13, v3
	v_mov_b32_e32 v14, v3
	v_mov_b64_e32 v[66:67], v[16:17]
	v_mov_b64_e32 v[34:35], v[16:17]
	v_mov_b64_e32 v[82:83], v[16:17]
	s_or_b32 s31, s31, s29
	s_or_b32 s67, s29, 3
	v_mov_b64_e32 v[64:65], v[14:15]
	v_mov_b64_e32 v[62:63], v[12:13]
	v_mov_b64_e32 v[60:61], v[10:11]
	v_mov_b64_e32 v[58:59], v[8:9]
	v_mov_b64_e32 v[56:57], v[6:7]
	v_mov_b64_e32 v[54:55], v[4:5]
	v_mov_b64_e32 v[52:53], v[2:3]
	v_mov_b64_e32 v[32:33], v[14:15]
	v_mov_b64_e32 v[30:31], v[12:13]
	v_mov_b64_e32 v[28:29], v[10:11]
	v_mov_b64_e32 v[26:27], v[8:9]
	v_mov_b64_e32 v[24:25], v[6:7]
	v_mov_b64_e32 v[22:23], v[4:5]
	v_mov_b64_e32 v[20:21], v[2:3]
	v_mov_b64_e32 v[80:81], v[14:15]
	v_mov_b64_e32 v[78:79], v[12:13]
	v_mov_b64_e32 v[76:77], v[10:11]
	v_mov_b64_e32 v[74:75], v[8:9]
	v_mov_b64_e32 v[72:73], v[6:7]
	v_mov_b64_e32 v[70:71], v[4:5]
	v_mov_b64_e32 v[68:69], v[2:3]
	v_mov_b64_e32 v[18:19], v[16:17]
	s_mov_b32 s30, 0
	s_sub_i32 s31, s31, s28
	s_sub_i32 s68, s67, s66
	v_mov_b32_e32 v183, 0
	v_mov_b32_e32 v187, 0
	v_mov_b64_e32 v[16:17], v[14:15]
	v_mov_b64_e32 v[14:15], v[12:13]
	v_mov_b64_e32 v[12:13], v[10:11]
	v_mov_b64_e32 v[10:11], v[8:9]
	v_mov_b64_e32 v[8:9], v[6:7]
	v_mov_b64_e32 v[6:7], v[4:5]
	v_mov_b64_e32 v[4:5], v[2:3]
	s_mov_b32 s80, 0x48000
	s_mov_b32 s81, 0
	s_mov_b32 s82, 0x100000
	s_mov_b32 s83, 0
	s_add_i32 s74, s19, -1
	s_lshl_b32 s78, s74, 7
	s_mov_b32 s79, 0
	v_mad_u64_u32 v[210:211], s[76:77], s74, v231, v[180:181]
	v_lshl_add_u64 v[212:213], s[78:79], 1, v[178:179]
	v_lshl_add_u64 v[234:235], v[210:211], 0, s[80:81]
	v_lshl_add_u64 v[236:237], v[212:213], 0, s[82:83]
	s_bitcmp1_b32 s19, 0
	s_cbranch_scc1 .Lattn_pro_ra
	global_load_dwordx4 v[194:197], v[210:211], off
	global_load_dwordx4 v[198:201], v[212:213], off
	global_load_dwordx4 v[202:205], v[234:235], off
	global_load_dwordx4 v[206:209], v[236:237], off
	s_branch .Lattn_pro_done
.Lattn_pro_ra:
	global_load_dwordx4 v[116:119], v[210:211], off
	global_load_dwordx4 v[120:123], v[212:213], off
	global_load_dwordx4 v[124:127], v[234:235], off
	global_load_dwordx4 v[128:131], v[236:237], off
.Lattn_pro_done:
	s_waitcnt lgkmcnt(0)
	s_barrier
	s_cmp_lg_u32 s19, 0
	s_cselect_b64 s[28:29], -1, 0
	s_cmp_eq_u32 s19, 0
	s_cbranch_scc1 .LBB0_685
.LBB0_684:
	s_add_i32 s74, s19, -2
	s_max_i32 s74, s74, 0
	s_lshl_b32 s78, s74, 7
	s_mov_b32 s79, 0
	v_mad_u64_u32 v[210:211], s[76:77], s74, v231, v[180:181]
	v_lshl_add_u64 v[212:213], s[78:79], 1, v[178:179]
	v_lshl_add_u64 v[234:235], v[210:211], 0, s[80:81]
	v_lshl_add_u64 v[236:237], v[212:213], 0, s[82:83]
	s_bitcmp1_b32 s19, 0
	s_cbranch_scc1 .Lattn_top_rb
	global_load_dwordx4 v[116:119], v[210:211], off
	global_load_dwordx4 v[120:123], v[212:213], off
	global_load_dwordx4 v[124:127], v[234:235], off
	global_load_dwordx4 v[128:131], v[236:237], off
	s_branch .LBB0_685
.Lattn_top_rb:
	global_load_dwordx4 v[194:197], v[210:211], off
	global_load_dwordx4 v[198:201], v[212:213], off
	global_load_dwordx4 v[202:205], v[234:235], off
	global_load_dwordx4 v[206:209], v[236:237], off

.LBB0_696:
	s_xor_b32 s30, s30, 1
	s_and_b64 vcc, exec, s[28:29]
	s_cbranch_vccz .LBB0_698
	s_mul_i32 s28, s30, 0x8a00
	s_add_i32 s28, s28, 0
	v_add_u32_e32 v2, s28, v176
	v_add_u32_e32 v84, s28, v182
	v_add_u32_e32 v85, 0x4800, v84
	s_bitcmp1_b32 s19, 0
	s_cbranch_scc0 .Lattn_bot_rb
	s_waitcnt vmcnt(7)
	ds_write_b128 v2, v[116:119]
	s_waitcnt vmcnt(6)
	ds_write2_b64 v85, v[120:121], v[122:123] offset1:1
	s_waitcnt vmcnt(5)
	ds_write_b128 v2, v[124:127] offset:9216
	v_add_u32_e32 v2, 0x6900, v84
	s_waitcnt vmcnt(4)
	ds_write2_b64 v2, v[128:129], v[130:131] offset1:1
	s_branch .LBB0_698
.Lattn_bot_rb:
	s_waitcnt vmcnt(7)
	ds_write_b128 v2, v[194:197]
	s_waitcnt vmcnt(6)
	ds_write2_b64 v85, v[198:199], v[200:201] offset1:1
	s_waitcnt vmcnt(5)
	ds_write_b128 v2, v[202:205] offset:9216
	v_add_u32_e32 v2, 0x6900, v84
	s_waitcnt vmcnt(4)
	ds_write2_b64 v2, v[206:207], v[208:209] offset1:1

.LBB0_866:
	v_lshl_add_u32 v176, s59, 8, v1
	v_ashrrev_i32_e32 v177, 31, v176
	v_lshl_add_u64 v[132:133], v[176:177], 4, s[24:25]
	v_mov_b64_e32 v[192:193], v[132:133]
	global_load_dwordx4 v[132:135], v[132:133], off
	global_load_dwordx4 v[188:191], v[192:193], off offset:256
	global_load_dwordx4 v[210:213], v[192:193], off offset:512
	global_load_dwordx4 v[234:237], v[192:193], off offset:768
	global_load_dwordx4 v[238:241], v[192:193], off offset:2048
	global_load_dwordx4 v[242:245], v[192:193], off offset:2304
	global_load_dwordx4 v[246:249], v[192:193], off offset:2560
	s_mov_b32 s18, 0xf800000
	v_or_b32_e32 v166, 16, v176
	v_ashrrev_i32_e32 v167, 31, v166
	v_or_b32_e32 v162, 32, v176
	v_ashrrev_i32_e32 v163, 31, v162
	v_or_b32_e32 v156, 48, v176
	v_ashrrev_i32_e32 v157, 31, v156
	v_add_u32_e32 v178, 0x90, v176
	v_ashrrev_i32_e32 v179, 31, v178
	v_add_u32_e32 v180, 0xa0, v176
	v_ashrrev_i32_e32 v181, 31, v180
	v_add_u32_e32 v182, 0xb0, v176
	v_ashrrev_i32_e32 v183, 31, v182
	v_mov_b32_e32 v186, v120
	v_mov_b32_e32 v187, v128
	v_mov_b32_e32 v128, v121
	s_waitcnt vmcnt(6)
	v_mov_b32_e32 v152, v133
	v_mov_b32_e32 v153, v134
	v_mov_b32_e32 v133, v135
	v_pk_add_f32 v[132:133], v[152:153], v[132:133]
	s_nop 0
	v_add_f32_e32 v132, v132, v133
	v_fmamk_f32 v132, v132, 0x3a800000, v215
	v_cmp_gt_f32_e32 vcc, s18, v132
	v_mul_f32_e32 v133, 0x4f800000, v132
	s_nop 0
	v_cndmask_b32_e32 v132, v132, v133, vcc
	v_sqrt_f32_e32 v133, v132
	s_nop 0
	v_add_u32_e32 v134, -1, v133
	v_fma_f32 v135, -v134, v133, v132
	v_cmp_ge_f32_e64 s[4:5], 0, v135
	v_add_u32_e32 v135, 1, v133
	s_nop 0
	v_cndmask_b32_e64 v134, v133, v134, s[4:5]
	v_fma_f32 v133, -v135, v133, v132
	v_cmp_lt_f32_e64 s[4:5], 0, v133
	s_nop 1
	v_cndmask_b32_e64 v133, v134, v135, s[4:5]
	v_mul_f32_e32 v134, 0x37800000, v133
	v_cndmask_b32_e32 v133, v133, v134, vcc
	v_cmp_class_f32_e32 vcc, v132, v216
	s_nop 1
	v_cndmask_b32_e32 v132, v133, v132, vcc
	v_div_scale_f32 v133, s[4:5], v132, v132, 1.0
	v_rcp_f32_e32 v134, v133
	s_nop 0
	v_fma_f32 v135, -v133, v134, 1.0
	v_fmac_f32_e32 v134, v135, v134
	v_div_scale_f32 v135, vcc, 1.0, v132, 1.0
	v_mul_f32_e32 v146, v135, v134
	v_fma_f32 v148, -v133, v146, v135
	v_fmac_f32_e32 v146, v148, v134
	v_fma_f32 v133, -v133, v146, v135
	v_div_fmas_f32 v133, v133, v134, v146
	v_div_fixup_f32 v158, v133, v132, 1.0
	v_lshl_add_u64 v[132:133], v[166:167], 4, s[24:25]
	v_pk_mul_f32 v[186:187], v[186:187], v[158:159] op_sel_hi:[1,0]
	s_waitcnt vmcnt(5)
	v_mov_b64_e32 v[132:133], v[188:189]
	v_mov_b64_e32 v[134:135], v[190:191]
	global_load_dwordx4 v[188:191], v[192:193], off offset:2816
	v_mov_b32_e32 v152, v133
	v_mov_b32_e32 v153, v134
	v_mov_b32_e32 v133, v135
	v_pk_add_f32 v[132:133], v[152:153], v[132:133]
	v_mul_f32_e32 v120, 0xbfb8aa3b, v187
	v_add_f32_e32 v132, v132, v133
	v_fmamk_f32 v132, v132, 0x3a800000, v215
	v_cmp_gt_f32_e32 vcc, s18, v132
	v_mul_f32_e32 v133, 0x4f800000, v132
	v_exp_f32_e32 v120, v120
	v_cndmask_b32_e32 v132, v132, v133, vcc
	v_sqrt_f32_e32 v133, v132
	v_add_f32_e32 v120, 1.0, v120
	v_rcp_f32_e32 v120, v120
	v_add_u32_e32 v134, -1, v133
	v_fma_f32 v135, -v134, v133, v132
	v_cmp_ge_f32_e64 s[4:5], 0, v135
	v_add_u32_e32 v135, 1, v133
	v_mul_f32_e32 v120, v187, v120
	v_cndmask_b32_e64 v134, v133, v134, s[4:5]
	v_fma_f32 v133, -v135, v133, v132
	v_cmp_lt_f32_e64 s[4:5], 0, v133
	v_mov_b32_e32 v187, v124
	v_mov_b32_e32 v124, v117
	v_cndmask_b32_e64 v133, v134, v135, s[4:5]
	v_mul_f32_e32 v134, 0x37800000, v133
	v_cndmask_b32_e32 v133, v133, v134, vcc
	v_cmp_class_f32_e32 vcc, v132, v216
	s_nop 1
	v_cndmask_b32_e32 v132, v133, v132, vcc
	v_div_scale_f32 v133, s[4:5], v132, v132, 1.0
	v_rcp_f32_e32 v134, v133
	s_nop 0
	v_fma_f32 v135, -v133, v134, 1.0
	v_fmac_f32_e32 v134, v135, v134
	v_div_scale_f32 v135, vcc, 1.0, v132, 1.0
	v_mul_f32_e32 v146, v135, v134
	v_fma_f32 v148, -v133, v146, v135
	v_fmac_f32_e32 v146, v148, v134
	v_fma_f32 v133, -v133, v146, v135
	v_div_fmas_f32 v133, v133, v134, v146
	v_div_fixup_f32 v154, v133, v132, 1.0
	v_lshl_add_u64 v[132:133], v[162:163], 4, s[24:25]
	s_waitcnt vmcnt(5)
	v_mov_b64_e32 v[132:133], v[210:211]
	v_mov_b64_e32 v[134:135], v[212:213]
	v_mov_b32_e32 v152, v133
	v_mov_b32_e32 v153, v134
	v_mov_b32_e32 v133, v135
	v_pk_add_f32 v[132:133], v[152:153], v[132:133]
	s_nop 0
	v_add_f32_e32 v132, v132, v133
	v_fmamk_f32 v132, v132, 0x3a800000, v215
	v_cmp_gt_f32_e32 vcc, s18, v132
	v_mul_f32_e32 v133, 0x4f800000, v132
	s_nop 0
	v_cndmask_b32_e32 v132, v132, v133, vcc
	v_sqrt_f32_e32 v133, v132
	s_nop 0
	v_add_u32_e32 v134, -1, v133
	v_fma_f32 v135, -v134, v133, v132
	v_cmp_ge_f32_e64 s[4:5], 0, v135
	v_add_u32_e32 v135, 1, v133
	s_nop 0
	v_cndmask_b32_e64 v134, v133, v134, s[4:5]
	v_fma_f32 v133, -v135, v133, v132
	v_cmp_lt_f32_e64 s[4:5], 0, v133
	s_nop 1
	v_cndmask_b32_e64 v133, v134, v135, s[4:5]
	v_mul_f32_e32 v134, 0x37800000, v133
	v_cndmask_b32_e32 v133, v133, v134, vcc
	v_cmp_class_f32_e32 vcc, v132, v216
	s_nop 1
	v_cndmask_b32_e32 v132, v133, v132, vcc
	v_div_scale_f32 v133, s[4:5], v132, v132, 1.0
	v_rcp_f32_e32 v134, v133
	s_nop 0
	v_fma_f32 v135, -v133, v134, 1.0
	v_fmac_f32_e32 v134, v135, v134
	v_div_scale_f32 v135, vcc, 1.0, v132, 1.0
	v_mul_f32_e32 v146, v135, v134
	v_fma_f32 v148, -v133, v146, v135
	v_fmac_f32_e32 v146, v148, v134
	v_fma_f32 v133, -v133, v146, v135
	v_div_fmas_f32 v133, v133, v134, v146
	v_div_fixup_f32 v150, v133, v132, 1.0
	v_lshl_add_u64 v[132:133], v[156:157], 4, s[24:25]
	s_waitcnt vmcnt(4)
	v_mov_b64_e32 v[132:133], v[234:235]
	v_mov_b64_e32 v[134:135], v[236:237]
	v_mov_b32_e32 v152, v133
	v_mov_b32_e32 v153, v134
	v_mov_b32_e32 v133, v135
	v_pk_add_f32 v[132:133], v[152:153], v[132:133]
	v_add_u32_e32 v152, 0x80, v176
	v_add_f32_e32 v132, v132, v133
	v_fmamk_f32 v132, v132, 0x3a800000, v215
	v_cmp_gt_f32_e32 vcc, s18, v132
	v_mul_f32_e32 v133, 0x4f800000, v132
	v_ashrrev_i32_e32 v153, 31, v152
	v_cndmask_b32_e32 v132, v132, v133, vcc
	v_sqrt_f32_e32 v133, v132
	s_nop 0
	v_add_u32_e32 v134, -1, v133
	v_fma_f32 v135, -v134, v133, v132
	v_cmp_ge_f32_e64 s[4:5], 0, v135
	v_add_u32_e32 v135, 1, v133
	s_nop 0
	v_cndmask_b32_e64 v134, v133, v134, s[4:5]
	v_fma_f32 v133, -v135, v133, v132
	v_cmp_lt_f32_e64 s[4:5], 0, v133
	s_nop 1
	v_cndmask_b32_e64 v133, v134, v135, s[4:5]
	v_mul_f32_e32 v134, 0x37800000, v133
	v_cndmask_b32_e32 v133, v133, v134, vcc
	v_cmp_class_f32_e32 vcc, v132, v216
	s_nop 1
	v_cndmask_b32_e32 v132, v133, v132, vcc
	v_div_scale_f32 v133, s[4:5], v132, v132, 1.0
	v_rcp_f32_e32 v134, v133
	s_nop 0
	v_fma_f32 v135, -v133, v134, 1.0
	v_fmac_f32_e32 v134, v135, v134
	v_div_scale_f32 v135, vcc, 1.0, v132, 1.0
	v_mul_f32_e32 v146, v135, v134
	v_fma_f32 v148, -v133, v146, v135
	v_fmac_f32_e32 v146, v148, v134
	v_fma_f32 v133, -v133, v146, v135
	v_div_fmas_f32 v133, v133, v134, v146
	v_div_fixup_f32 v148, v133, v132, 1.0
	v_lshl_add_u64 v[132:133], v[152:153], 4, s[24:25]
	s_waitcnt vmcnt(3)
	v_mov_b64_e32 v[132:133], v[238:239]
	v_mov_b64_e32 v[134:135], v[240:241]
	v_mov_b32_e32 v160, v133
	v_mov_b32_e32 v161, v134
	v_mov_b32_e32 v133, v135
	v_pk_add_f32 v[132:133], v[160:161], v[132:133]
	s_nop 0
	v_add_f32_e32 v132, v132, v133
	v_fmamk_f32 v132, v132, 0x3a800000, v215
	v_cmp_gt_f32_e32 vcc, s18, v132
	v_mul_f32_e32 v133, 0x4f800000, v132
	s_nop 0
	v_cndmask_b32_e32 v132, v132, v133, vcc
	v_sqrt_f32_e32 v133, v132
	s_nop 0
	v_add_u32_e32 v134, -1, v133
	v_fma_f32 v135, -v134, v133, v132
	v_cmp_ge_f32_e64 s[4:5], 0, v135
	v_add_u32_e32 v135, 1, v133
	s_nop 0
	v_cndmask_b32_e64 v134, v133, v134, s[4:5]
	v_fma_f32 v133, -v135, v133, v132
	v_cmp_lt_f32_e64 s[4:5], 0, v133
	s_nop 1
	v_cndmask_b32_e64 v133, v134, v135, s[4:5]
	v_mul_f32_e32 v134, 0x37800000, v133
	v_cndmask_b32_e32 v133, v133, v134, vcc
	v_cmp_class_f32_e32 vcc, v132, v216
	s_nop 1
	v_cndmask_b32_e32 v132, v133, v132, vcc
	v_div_scale_f32 v133, s[4:5], v132, v132, 1.0
	v_rcp_f32_e32 v134, v133
	s_nop 0
	v_fma_f32 v135, -v133, v134, 1.0
	v_fmac_f32_e32 v134, v135, v134
	v_div_scale_f32 v135, vcc, 1.0, v132, 1.0
	v_mul_f32_e32 v146, v135, v134
	v_fma_f32 v153, -v133, v146, v135
	v_fmac_f32_e32 v146, v153, v134
	v_fma_f32 v133, -v133, v146, v135
	v_div_fmas_f32 v133, v133, v134, v146
	v_div_fixup_f32 v146, v133, v132, 1.0
	v_lshl_add_u64 v[132:133], v[178:179], 4, s[24:25]
	s_waitcnt vmcnt(2)
	v_mov_b64_e32 v[132:133], v[242:243]
	v_mov_b64_e32 v[134:135], v[244:245]
	v_mov_b32_e32 v160, v133
	v_mov_b32_e32 v161, v134
	v_mov_b32_e32 v133, v135
	v_pk_add_f32 v[132:133], v[160:161], v[132:133]
	s_nop 0
	v_add_f32_e32 v132, v132, v133
	v_fmamk_f32 v132, v132, 0x3a800000, v215
	v_cmp_gt_f32_e32 vcc, s18, v132
	v_mul_f32_e32 v133, 0x4f800000, v132
	s_nop 0
	v_cndmask_b32_e32 v132, v132, v133, vcc
	v_sqrt_f32_e32 v133, v132
	s_nop 0
	v_add_u32_e32 v134, -1, v133
	v_fma_f32 v135, -v134, v133, v132
	v_cmp_ge_f32_e64 s[4:5], 0, v135
	v_add_u32_e32 v135, 1, v133
	s_nop 0
	v_cndmask_b32_e64 v134, v133, v134, s[4:5]
	v_fma_f32 v133, -v135, v133, v132
	v_cmp_lt_f32_e64 s[4:5], 0, v133
	s_nop 1
	v_cndmask_b32_e64 v133, v134, v135, s[4:5]
	v_mul_f32_e32 v134, 0x37800000, v133
	v_cndmask_b32_e32 v133, v133, v134, vcc
	v_cmp_class_f32_e32 vcc, v132, v216
	s_nop 1
	v_cndmask_b32_e32 v132, v133, v132, vcc
	v_div_scale_f32 v133, s[4:5], v132, v132, 1.0
	v_rcp_f32_e32 v134, v133
	s_nop 0
	v_fma_f32 v135, -v133, v134, 1.0
	v_fmac_f32_e32 v134, v135, v134
	v_div_scale_f32 v135, vcc, 1.0, v132, 1.0
	v_mul_f32_e32 v153, v135, v134
	v_fma_f32 v155, -v133, v153, v135
	v_fmac_f32_e32 v153, v155, v134
	v_fma_f32 v133, -v133, v153, v135
	v_div_fmas_f32 v133, v133, v134, v153
	v_div_fixup_f32 v160, v133, v132, 1.0
	v_lshl_add_u64 v[132:133], v[180:181], 4, s[24:25]
	s_waitcnt vmcnt(1)
	v_mov_b64_e32 v[132:133], v[246:247]
	v_mov_b64_e32 v[134:135], v[248:249]
	v_mov_b32_e32 v164, v133
	v_mov_b32_e32 v165, v134
	v_mov_b32_e32 v133, v135
	v_pk_add_f32 v[132:133], v[164:165], v[132:133]
	s_nop 0
	v_add_f32_e32 v132, v132, v133
	v_fmamk_f32 v132, v132, 0x3a800000, v215
	v_cmp_gt_f32_e32 vcc, s18, v132
	v_mul_f32_e32 v133, 0x4f800000, v132
	s_nop 0
	v_cndmask_b32_e32 v132, v132, v133, vcc
	v_sqrt_f32_e32 v133, v132
	s_nop 0
	v_add_u32_e32 v134, -1, v133
	v_fma_f32 v135, -v134, v133, v132
	v_cmp_ge_f32_e64 s[4:5], 0, v135
	v_add_u32_e32 v135, 1, v133
	s_nop 0
	v_cndmask_b32_e64 v134, v133, v134, s[4:5]
	v_fma_f32 v133, -v135, v133, v132
	v_cmp_lt_f32_e64 s[4:5], 0, v133
	s_nop 1
	v_cndmask_b32_e64 v133, v134, v135, s[4:5]
	v_mul_f32_e32 v134, 0x37800000, v133
	v_cndmask_b32_e32 v133, v133, v134, vcc
	v_cmp_class_f32_e32 vcc, v132, v216
	s_nop 1
	v_cndmask_b32_e32 v132, v133, v132, vcc
	v_div_scale_f32 v133, s[4:5], v132, v132, 1.0
	v_rcp_f32_e32 v134, v133
	s_nop 0
	v_fma_f32 v135, -v133, v134, 1.0
	v_fmac_f32_e32 v134, v135, v134
	v_div_scale_f32 v135, vcc, 1.0, v132, 1.0
	v_mul_f32_e32 v153, v135, v134
	v_fma_f32 v155, -v133, v153, v135
	v_fmac_f32_e32 v153, v155, v134
	v_fma_f32 v133, -v133, v153, v135
	v_div_fmas_f32 v133, v133, v134, v153
	v_div_fixup_f32 v164, v133, v132, 1.0
	v_lshl_add_u64 v[132:133], v[182:183], 4, s[24:25]
	s_waitcnt vmcnt(0)
	v_mov_b64_e32 v[132:133], v[188:189]
	v_mov_b64_e32 v[134:135], v[190:191]
	v_mov_b32_e32 v184, v133
	v_mov_b32_e32 v185, v134
	v_mov_b32_e32 v133, v135
	v_pk_add_f32 v[132:133], v[184:185], v[132:133]
	v_lshl_or_b32 v184, s58, 7, v149
	v_add_f32_e32 v132, v132, v133
	v_fmamk_f32 v132, v132, 0x3a800000, v215
	v_cmp_gt_f32_e32 vcc, s18, v132
	v_mul_f32_e32 v133, 0x4f800000, v132
	v_ashrrev_i32_e32 v185, 31, v184
	v_cndmask_b32_e32 v132, v132, v133, vcc
	v_sqrt_f32_e32 v133, v132
	s_movk_i32 s18, 0x1600
	v_add_u32_e32 v134, -1, v133
	v_fma_f32 v135, -v134, v133, v132
	v_cmp_ge_f32_e64 s[4:5], 0, v135
	v_add_u32_e32 v135, 1, v133
	s_nop 0
	v_cndmask_b32_e64 v134, v133, v134, s[4:5]
	v_fma_f32 v133, -v135, v133, v132
	v_cmp_lt_f32_e64 s[4:5], 0, v133
	s_nop 1
	v_cndmask_b32_e64 v133, v134, v135, s[4:5]
	v_mul_f32_e32 v134, 0x37800000, v133
	v_cndmask_b32_e32 v133, v133, v134, vcc
	v_cmp_class_f32_e32 vcc, v132, v216
	s_nop 1
	v_cndmask_b32_e32 v132, v133, v132, vcc
	v_div_scale_f32 v133, s[4:5], v132, v132, 1.0
	v_rcp_f32_e32 v134, v133
	s_nop 0
	v_fma_f32 v135, -v133, v134, 1.0
	v_fmac_f32_e32 v134, v135, v134
	v_div_scale_f32 v135, vcc, 1.0, v132, 1.0
	v_mul_f32_e32 v153, v135, v134
	v_fma_f32 v155, -v133, v153, v135
	v_fmac_f32_e32 v153, v155, v134
	v_fma_f32 v133, -v133, v153, v135
	v_div_fmas_f32 v133, v133, v134, v153
	v_div_fixup_f32 v132, v133, v132, 1.0
	v_mul_f32_e32 v133, v186, v120
	v_mov_b32_e32 v186, v116
	v_pk_mul_f32 v[186:187], v[186:187], v[158:159] op_sel_hi:[1,0]
	v_pk_mul_f32 v[120:121], v[128:129], v[158:159] op_sel_hi:[1,0]
	v_mul_f32_e32 v116, 0xbfb8aa3b, v187
	v_exp_f32_e32 v116, v116
	v_mov_b64_e32 v[134:135], s[22:23]
	v_mad_i64_i32 v[176:177], s[4:5], v176, s18, v[134:135]
	v_add_f32_e32 v116, 1.0, v116
	v_rcp_f32_e32 v116, v116
	s_andn2_b64 vcc, exec, s[42:43]
	v_mul_f32_e32 v116, v187, v116
	v_mul_f32_e32 v153, v186, v116
	v_mul_f32_e32 v116, 0xbfb8aa3b, v121
	v_exp_f32_e32 v116, v116
	s_nop 0
	v_add_f32_e32 v116, 1.0, v116
	v_rcp_f32_e32 v116, v116
	s_nop 0
	v_mul_f32_e32 v116, v121, v116
	v_mul_f32_e32 v120, v120, v116
	v_pk_mul_f32 v[116:117], v[124:125], v[158:159] op_sel_hi:[1,0]
	s_nop 0
	v_mul_f32_e32 v121, 0xbfb8aa3b, v117
	v_exp_f32_e32 v121, v121
	s_nop 0
	v_add_f32_e32 v121, 1.0, v121
	v_rcp_f32_e32 v121, v121
	s_nop 0
	v_mul_f32_e32 v117, v117, v121
	v_mul_f32_e32 v121, v116, v117
	v_mov_b32_e32 v116, v122
	v_mov_b32_e32 v117, v130
	v_pk_mul_f32 v[116:117], v[116:117], v[158:159] op_sel_hi:[1,0]
	v_mov_b32_e32 v130, v123
	v_mul_f32_e32 v122, 0xbfb8aa3b, v117
	v_exp_f32_e32 v122, v122
	s_nop 0
	v_add_f32_e32 v122, 1.0, v122
	v_rcp_f32_e32 v122, v122
	s_nop 0
	v_mul_f32_e32 v117, v117, v122
	v_mul_f32_e32 v124, v116, v117
	v_mov_b32_e32 v116, v118
	v_mov_b32_e32 v117, v126
	v_pk_mul_f32 v[116:117], v[116:117], v[158:159] op_sel_hi:[1,0]
	v_mov_b32_e32 v126, v119
	v_mul_f32_e32 v118, 0xbfb8aa3b, v117
	v_exp_f32_e32 v118, v118
	s_nop 0
	v_add_f32_e32 v118, 1.0, v118
	v_rcp_f32_e32 v118, v118
	s_nop 0
	v_mul_f32_e32 v117, v117, v118
	v_mul_f32_e32 v125, v116, v117
	v_pk_mul_f32 v[116:117], v[130:131], v[158:159] op_sel_hi:[1,0]
	s_nop 0
	v_mul_f32_e32 v118, 0xbfb8aa3b, v117
	v_exp_f32_e32 v118, v118
	s_nop 0
	v_add_f32_e32 v118, 1.0, v118
	v_rcp_f32_e32 v118, v118
	s_nop 0
	v_mul_f32_e32 v117, v117, v118
	v_mul_f32_e32 v128, v116, v117
	v_pk_mul_f32 v[116:117], v[126:127], v[158:159] op_sel_hi:[1,0]
	s_nop 0
	v_mul_f32_e32 v118, 0xbfb8aa3b, v117
	v_exp_f32_e32 v118, v118
	s_nop 0
	v_add_f32_e32 v118, 1.0, v118
	v_rcp_f32_e32 v118, v118
	s_nop 0
	v_mul_f32_e32 v117, v117, v118
	v_mul_f32_e32 v126, v116, v117
	v_lshlrev_b64 v[116:117], 1, v[184:185]
	v_lshl_add_u64 v[122:123], v[176:177], 0, v[116:117]
	v_cvt_pk_bf16_f32 v118, v133, v120
	v_cvt_pk_bf16_f32 v119, v124, v128
	v_cvt_pk_bf16_f32 v120, v153, v121
	v_cvt_pk_bf16_f32 v121, v125, v126
	global_store_dwordx4 v[122:123], v[118:121], off
	s_nop 1
	v_mov_b32_e32 v120, v104
	v_mov_b32_e32 v121, v112
	v_pk_mul_f32 v[120:121], v[120:121], v[154:155] op_sel_hi:[1,0]
	v_mov_b32_e32 v112, v105
	v_mul_f32_e32 v104, 0xbfb8aa3b, v121
	v_exp_f32_e32 v104, v104
	v_mad_i64_i32 v[118:119], s[4:5], v166, s18, v[134:135]
	v_add_f32_e32 v104, 1.0, v104
	v_rcp_f32_e32 v104, v104
	s_nop 0
	v_mul_f32_e32 v104, v121, v104
	v_mul_f32_e32 v122, v120, v104
	v_mov_b32_e32 v120, v100
	v_mov_b32_e32 v121, v108
	v_pk_mul_f32 v[120:121], v[120:121], v[154:155] op_sel_hi:[1,0]
	v_pk_mul_f32 v[104:105], v[112:113], v[154:155] op_sel_hi:[1,0]
	v_mul_f32_e32 v100, 0xbfb8aa3b, v121
	v_exp_f32_e32 v100, v100
	v_mov_b32_e32 v108, v101
	v_add_f32_e32 v100, 1.0, v100
	v_rcp_f32_e32 v100, v100
	s_nop 0
	v_mul_f32_e32 v100, v121, v100
	v_mul_f32_e32 v120, v120, v100
	v_mul_f32_e32 v100, 0xbfb8aa3b, v105
	v_exp_f32_e32 v100, v100
	s_nop 0
	v_add_f32_e32 v100, 1.0, v100
	v_rcp_f32_e32 v100, v100
	s_nop 0
	v_mul_f32_e32 v100, v105, v100
	v_mul_f32_e32 v112, v104, v100
	v_pk_mul_f32 v[100:101], v[108:109], v[154:155] op_sel_hi:[1,0]
	s_nop 0
	v_mul_f32_e32 v104, 0xbfb8aa3b, v101
	v_exp_f32_e32 v104, v104
	s_nop 0
	v_add_f32_e32 v104, 1.0, v104
	v_rcp_f32_e32 v104, v104
	s_nop 0
	v_mul_f32_e32 v101, v101, v104
	v_mul_f32_e32 v108, v100, v101
	v_mov_b32_e32 v100, v106
	v_mov_b32_e32 v101, v114
	v_pk_mul_f32 v[100:101], v[100:101], v[154:155] op_sel_hi:[1,0]
	v_mov_b32_e32 v114, v107
	v_mul_f32_e32 v104, 0xbfb8aa3b, v101
	v_exp_f32_e32 v104, v104
	s_nop 0
	v_add_f32_e32 v104, 1.0, v104
	v_rcp_f32_e32 v104, v104
	s_nop 0
	v_mul_f32_e32 v101, v101, v104
	v_mul_f32_e32 v106, v100, v101
	v_mov_b32_e32 v100, v102
	v_mov_b32_e32 v101, v110
	v_pk_mul_f32 v[100:101], v[100:101], v[154:155] op_sel_hi:[1,0]
	v_mov_b32_e32 v110, v103
	v_mul_f32_e32 v102, 0xbfb8aa3b, v101
	v_exp_f32_e32 v102, v102
	v_lshl_add_u64 v[104:105], v[118:119], 0, v[116:117]
	v_add_f32_e32 v102, 1.0, v102
	v_rcp_f32_e32 v102, v102
	s_nop 0
	v_mul_f32_e32 v101, v101, v102
	v_mul_f32_e32 v109, v100, v101
	v_pk_mul_f32 v[100:101], v[114:115], v[154:155] op_sel_hi:[1,0]
	s_nop 0
	v_mul_f32_e32 v102, 0xbfb8aa3b, v101
	v_exp_f32_e32 v102, v102
	s_nop 0
	v_add_f32_e32 v102, 1.0, v102
	v_rcp_f32_e32 v102, v102
	s_nop 0
	v_mul_f32_e32 v101, v101, v102
	v_mul_f32_e32 v102, v100, v101
	v_pk_mul_f32 v[100:101], v[110:111], v[154:155] op_sel_hi:[1,0]
	s_nop 0
	v_mul_f32_e32 v103, 0xbfb8aa3b, v101
	v_exp_f32_e32 v103, v103
	s_nop 0
	v_add_f32_e32 v103, 1.0, v103
	v_rcp_f32_e32 v103, v103
	s_nop 0
	v_mul_f32_e32 v101, v101, v103
	v_mul_f32_e32 v103, v100, v101
	v_cvt_pk_bf16_f32 v100, v122, v112
	v_cvt_pk_bf16_f32 v101, v106, v102
	v_cvt_pk_bf16_f32 v102, v120, v108
	v_cvt_pk_bf16_f32 v103, v109, v103
	global_store_dwordx4 v[104:105], v[100:103], off
	s_nop 1
	v_mov_b32_e32 v102, v88
	v_mov_b32_e32 v103, v96
	v_pk_mul_f32 v[102:103], v[102:103], v[150:151] op_sel_hi:[1,0]
	v_mov_b32_e32 v96, v89
	v_mul_f32_e32 v88, 0xbfb8aa3b, v103
	v_exp_f32_e32 v88, v88
	v_mad_i64_i32 v[100:101], s[4:5], v162, s18, v[134:135]
	v_add_f32_e32 v88, 1.0, v88
	v_rcp_f32_e32 v88, v88
	s_nop 0
	v_mul_f32_e32 v88, v103, v88
	v_mul_f32_e32 v104, v102, v88
	v_mov_b32_e32 v102, v84
	v_mov_b32_e32 v103, v92
	v_pk_mul_f32 v[102:103], v[102:103], v[150:151] op_sel_hi:[1,0]
	v_pk_mul_f32 v[88:89], v[96:97], v[150:151] op_sel_hi:[1,0]
	v_mul_f32_e32 v84, 0xbfb8aa3b, v103
	v_exp_f32_e32 v84, v84
	v_mov_b32_e32 v92, v85
	v_add_f32_e32 v84, 1.0, v84
	v_rcp_f32_e32 v84, v84
	s_nop 0
	v_mul_f32_e32 v84, v103, v84
	v_mul_f32_e32 v102, v102, v84
	v_mul_f32_e32 v84, 0xbfb8aa3b, v89
	v_exp_f32_e32 v84, v84
	s_nop 0
	v_add_f32_e32 v84, 1.0, v84
	v_rcp_f32_e32 v84, v84
	s_nop 0
	v_mul_f32_e32 v84, v89, v84
	v_mul_f32_e32 v96, v88, v84
	v_pk_mul_f32 v[84:85], v[92:93], v[150:151] op_sel_hi:[1,0]
	s_nop 0
	v_mul_f32_e32 v88, 0xbfb8aa3b, v85
	v_exp_f32_e32 v88, v88
	s_nop 0
	v_add_f32_e32 v88, 1.0, v88
	v_rcp_f32_e32 v88, v88
	s_nop 0
	v_mul_f32_e32 v85, v85, v88
	v_mul_f32_e32 v92, v84, v85
	v_mov_b32_e32 v84, v90
	v_mov_b32_e32 v85, v98
	v_pk_mul_f32 v[84:85], v[84:85], v[150:151] op_sel_hi:[1,0]
	v_mov_b32_e32 v98, v91
	v_mul_f32_e32 v88, 0xbfb8aa3b, v85
	v_exp_f32_e32 v88, v88
	s_nop 0
	v_add_f32_e32 v88, 1.0, v88
	v_rcp_f32_e32 v88, v88
	s_nop 0
	v_mul_f32_e32 v85, v85, v88
	v_mul_f32_e32 v90, v84, v85
	v_mov_b32_e32 v84, v86
	v_mov_b32_e32 v85, v94
	v_pk_mul_f32 v[84:85], v[84:85], v[150:151] op_sel_hi:[1,0]
	v_mov_b32_e32 v94, v87
	v_mul_f32_e32 v86, 0xbfb8aa3b, v85
	v_exp_f32_e32 v86, v86
	v_lshl_add_u64 v[88:89], v[100:101], 0, v[116:117]
	v_add_f32_e32 v86, 1.0, v86
	v_rcp_f32_e32 v86, v86
	s_nop 0
	v_mul_f32_e32 v85, v85, v86
	v_mul_f32_e32 v93, v84, v85
	v_pk_mul_f32 v[84:85], v[98:99], v[150:151] op_sel_hi:[1,0]
	s_nop 0
	v_mul_f32_e32 v86, 0xbfb8aa3b, v85
	v_exp_f32_e32 v86, v86
	s_nop 0
	v_add_f32_e32 v86, 1.0, v86
	v_rcp_f32_e32 v86, v86
	s_nop 0
	v_mul_f32_e32 v85, v85, v86
	v_mul_f32_e32 v86, v84, v85
	v_pk_mul_f32 v[84:85], v[94:95], v[150:151] op_sel_hi:[1,0]
	s_nop 0
	v_mul_f32_e32 v87, 0xbfb8aa3b, v85
	v_exp_f32_e32 v87, v87
	s_nop 0
	v_add_f32_e32 v87, 1.0, v87
	v_rcp_f32_e32 v87, v87
	s_nop 0
	v_mul_f32_e32 v85, v85, v87
	v_mul_f32_e32 v87, v84, v85
	v_cvt_pk_bf16_f32 v84, v104, v96
	v_cvt_pk_bf16_f32 v85, v90, v86
	v_cvt_pk_bf16_f32 v86, v102, v92
	v_cvt_pk_bf16_f32 v87, v93, v87
	global_store_dwordx4 v[88:89], v[84:87], off
	s_nop 1
	v_mov_b32_e32 v86, v72
	v_mov_b32_e32 v87, v80
	v_pk_mul_f32 v[86:87], v[86:87], v[148:149] op_sel_hi:[1,0]
	v_mov_b32_e32 v80, v73
	v_mul_f32_e32 v72, 0xbfb8aa3b, v87
	v_exp_f32_e32 v72, v72
	v_mad_i64_i32 v[84:85], s[4:5], v156, s18, v[134:135]
	v_add_f32_e32 v72, 1.0, v72
	v_rcp_f32_e32 v72, v72
	s_nop 0
	v_mul_f32_e32 v72, v87, v72
	v_mul_f32_e32 v88, v86, v72
	v_mov_b32_e32 v86, v68
	v_mov_b32_e32 v87, v76
	v_pk_mul_f32 v[86:87], v[86:87], v[148:149] op_sel_hi:[1,0]
	v_pk_mul_f32 v[72:73], v[80:81], v[148:149] op_sel_hi:[1,0]
	v_mul_f32_e32 v68, 0xbfb8aa3b, v87
	v_exp_f32_e32 v68, v68
	v_mov_b32_e32 v76, v69
	v_add_f32_e32 v68, 1.0, v68
	v_rcp_f32_e32 v68, v68
	s_nop 0
	v_mul_f32_e32 v68, v87, v68
	v_mul_f32_e32 v86, v86, v68
	v_mul_f32_e32 v68, 0xbfb8aa3b, v73
	v_exp_f32_e32 v68, v68
	s_nop 0
	v_add_f32_e32 v68, 1.0, v68
	v_rcp_f32_e32 v68, v68
	s_nop 0
	v_mul_f32_e32 v68, v73, v68
	v_mul_f32_e32 v80, v72, v68
	v_pk_mul_f32 v[68:69], v[76:77], v[148:149] op_sel_hi:[1,0]
	s_nop 0
	v_mul_f32_e32 v72, 0xbfb8aa3b, v69
	v_exp_f32_e32 v72, v72
	s_nop 0
	v_add_f32_e32 v72, 1.0, v72
	v_rcp_f32_e32 v72, v72
	s_nop 0
	v_mul_f32_e32 v69, v69, v72
	v_mul_f32_e32 v76, v68, v69
	v_mov_b32_e32 v68, v74
	v_mov_b32_e32 v69, v82
	v_pk_mul_f32 v[68:69], v[68:69], v[148:149] op_sel_hi:[1,0]
	v_mov_b32_e32 v82, v75
	v_mul_f32_e32 v72, 0xbfb8aa3b, v69
	v_exp_f32_e32 v72, v72
	s_nop 0
	v_add_f32_e32 v72, 1.0, v72
	v_rcp_f32_e32 v72, v72
	s_nop 0
	v_mul_f32_e32 v69, v69, v72
	v_mul_f32_e32 v74, v68, v69
	v_mov_b32_e32 v68, v70
	v_mov_b32_e32 v69, v78
	v_pk_mul_f32 v[68:69], v[68:69], v[148:149] op_sel_hi:[1,0]
	v_mov_b32_e32 v78, v71
	v_mul_f32_e32 v70, 0xbfb8aa3b, v69
	v_exp_f32_e32 v70, v70
	v_lshl_add_u64 v[72:73], v[84:85], 0, v[116:117]
	v_add_f32_e32 v70, 1.0, v70
	v_rcp_f32_e32 v70, v70
	s_nop 0
	v_mul_f32_e32 v69, v69, v70
	v_mul_f32_e32 v77, v68, v69
	v_pk_mul_f32 v[68:69], v[82:83], v[148:149] op_sel_hi:[1,0]
	s_nop 0
	v_mul_f32_e32 v70, 0xbfb8aa3b, v69
	v_exp_f32_e32 v70, v70
	s_nop 0
	v_add_f32_e32 v70, 1.0, v70
	v_rcp_f32_e32 v70, v70
	s_nop 0
	v_mul_f32_e32 v69, v69, v70
	v_mul_f32_e32 v70, v68, v69
	v_pk_mul_f32 v[68:69], v[78:79], v[148:149] op_sel_hi:[1,0]
	s_nop 0
	v_mul_f32_e32 v71, 0xbfb8aa3b, v69
	v_exp_f32_e32 v71, v71
	s_nop 0
	v_add_f32_e32 v71, 1.0, v71
	v_rcp_f32_e32 v71, v71
	s_nop 0
	v_mul_f32_e32 v69, v69, v71
	v_mul_f32_e32 v71, v68, v69
	v_cvt_pk_bf16_f32 v68, v88, v80
	v_cvt_pk_bf16_f32 v69, v74, v70
	v_cvt_pk_bf16_f32 v70, v86, v76
	v_cvt_pk_bf16_f32 v71, v77, v71
	global_store_dwordx4 v[72:73], v[68:71], off
	s_nop 1
	v_mov_b32_e32 v70, v56
	v_mov_b32_e32 v71, v64
	v_pk_mul_f32 v[70:71], v[70:71], v[146:147] op_sel_hi:[1,0]
	v_mov_b32_e32 v64, v57
	v_mul_f32_e32 v56, 0xbfb8aa3b, v71
	v_exp_f32_e32 v56, v56
	v_mad_i64_i32 v[68:69], s[4:5], v152, s18, v[134:135]
	v_add_f32_e32 v56, 1.0, v56
	v_rcp_f32_e32 v56, v56
	s_nop 0
	v_mul_f32_e32 v56, v71, v56
	v_mul_f32_e32 v72, v70, v56
	v_mov_b32_e32 v70, v52
	v_mov_b32_e32 v71, v60
	v_pk_mul_f32 v[70:71], v[70:71], v[146:147] op_sel_hi:[1,0]
	v_pk_mul_f32 v[56:57], v[64:65], v[146:147] op_sel_hi:[1,0]
	v_mul_f32_e32 v52, 0xbfb8aa3b, v71
	v_exp_f32_e32 v52, v52
	v_mov_b32_e32 v60, v53
	v_add_f32_e32 v52, 1.0, v52
	v_rcp_f32_e32 v52, v52
	s_nop 0
	v_mul_f32_e32 v52, v71, v52
	v_mul_f32_e32 v70, v70, v52
	v_mul_f32_e32 v52, 0xbfb8aa3b, v57
	v_exp_f32_e32 v52, v52
	s_nop 0
	v_add_f32_e32 v52, 1.0, v52
	v_rcp_f32_e32 v52, v52
	s_nop 0
	v_mul_f32_e32 v52, v57, v52
	v_mul_f32_e32 v64, v56, v52
	v_pk_mul_f32 v[52:53], v[60:61], v[146:147] op_sel_hi:[1,0]
	s_nop 0
	v_mul_f32_e32 v56, 0xbfb8aa3b, v53
	v_exp_f32_e32 v56, v56
	s_nop 0
	v_add_f32_e32 v56, 1.0, v56
	v_rcp_f32_e32 v56, v56
	s_nop 0
	v_mul_f32_e32 v53, v53, v56
	v_mul_f32_e32 v60, v52, v53
	v_mov_b32_e32 v52, v58
	v_mov_b32_e32 v53, v66
	v_pk_mul_f32 v[52:53], v[52:53], v[146:147] op_sel_hi:[1,0]
	v_mov_b32_e32 v66, v59
	v_mul_f32_e32 v56, 0xbfb8aa3b, v53
	v_exp_f32_e32 v56, v56
	s_nop 0
	v_add_f32_e32 v56, 1.0, v56
	v_rcp_f32_e32 v56, v56
	s_nop 0
	v_mul_f32_e32 v53, v53, v56
	v_mul_f32_e32 v58, v52, v53
	v_mov_b32_e32 v52, v54
	v_mov_b32_e32 v53, v62
	v_pk_mul_f32 v[52:53], v[52:53], v[146:147] op_sel_hi:[1,0]
	v_mov_b32_e32 v62, v55
	v_mul_f32_e32 v54, 0xbfb8aa3b, v53
	v_exp_f32_e32 v54, v54
	v_lshl_add_u64 v[56:57], v[68:69], 0, v[116:117]
	v_add_f32_e32 v54, 1.0, v54
	v_rcp_f32_e32 v54, v54
	s_nop 0
	v_mul_f32_e32 v53, v53, v54
	v_mul_f32_e32 v61, v52, v53
	v_pk_mul_f32 v[52:53], v[66:67], v[146:147] op_sel_hi:[1,0]
	s_nop 0
	v_mul_f32_e32 v54, 0xbfb8aa3b, v53
	v_exp_f32_e32 v54, v54
	s_nop 0
	v_add_f32_e32 v54, 1.0, v54
	v_rcp_f32_e32 v54, v54
	s_nop 0
	v_mul_f32_e32 v53, v53, v54
	v_mul_f32_e32 v54, v52, v53
	v_pk_mul_f32 v[52:53], v[62:63], v[146:147] op_sel_hi:[1,0]
	s_nop 0
	v_mul_f32_e32 v55, 0xbfb8aa3b, v53
	v_exp_f32_e32 v55, v55
	s_nop 0
	v_add_f32_e32 v55, 1.0, v55
	v_rcp_f32_e32 v55, v55
	s_nop 0
	v_mul_f32_e32 v53, v53, v55
	v_mul_f32_e32 v55, v52, v53
	v_cvt_pk_bf16_f32 v52, v72, v64
	v_cvt_pk_bf16_f32 v53, v58, v54
	v_cvt_pk_bf16_f32 v54, v70, v60
	v_cvt_pk_bf16_f32 v55, v61, v55
	global_store_dwordx4 v[56:57], v[52:55], off
	s_nop 1
	v_mov_b32_e32 v54, v40
	v_mov_b32_e32 v55, v48
	v_pk_mul_f32 v[54:55], v[54:55], v[160:161] op_sel_hi:[1,0]
	v_mov_b32_e32 v48, v41
	v_mul_f32_e32 v40, 0xbfb8aa3b, v55
	v_exp_f32_e32 v40, v40
	v_mad_i64_i32 v[52:53], s[4:5], v178, s18, v[134:135]
	v_add_f32_e32 v40, 1.0, v40
	v_rcp_f32_e32 v40, v40
	s_nop 0
	v_mul_f32_e32 v40, v55, v40
	v_mul_f32_e32 v56, v54, v40
	v_mov_b32_e32 v54, v36
	v_mov_b32_e32 v55, v44
	v_pk_mul_f32 v[54:55], v[54:55], v[160:161] op_sel_hi:[1,0]
	v_pk_mul_f32 v[40:41], v[48:49], v[160:161] op_sel_hi:[1,0]
	v_mul_f32_e32 v36, 0xbfb8aa3b, v55
	v_exp_f32_e32 v36, v36
	v_mov_b32_e32 v44, v37
	v_add_f32_e32 v36, 1.0, v36
	v_rcp_f32_e32 v36, v36
	s_nop 0
	v_mul_f32_e32 v36, v55, v36
	v_mul_f32_e32 v54, v54, v36
	v_mul_f32_e32 v36, 0xbfb8aa3b, v41
	v_exp_f32_e32 v36, v36
	s_nop 0
	v_add_f32_e32 v36, 1.0, v36
	v_rcp_f32_e32 v36, v36
	s_nop 0
	v_mul_f32_e32 v36, v41, v36
	v_mul_f32_e32 v48, v40, v36
	v_pk_mul_f32 v[36:37], v[44:45], v[160:161] op_sel_hi:[1,0]
	s_nop 0
	v_mul_f32_e32 v40, 0xbfb8aa3b, v37
	v_exp_f32_e32 v40, v40
	s_nop 0
	v_add_f32_e32 v40, 1.0, v40
	v_rcp_f32_e32 v40, v40
	s_nop 0
	v_mul_f32_e32 v37, v37, v40
	v_mul_f32_e32 v44, v36, v37
	v_mov_b32_e32 v36, v42
	v_mov_b32_e32 v37, v50
	v_pk_mul_f32 v[36:37], v[36:37], v[160:161] op_sel_hi:[1,0]
	v_mov_b32_e32 v50, v43
	v_mul_f32_e32 v40, 0xbfb8aa3b, v37
	v_exp_f32_e32 v40, v40
	s_nop 0
	v_add_f32_e32 v40, 1.0, v40
	v_rcp_f32_e32 v40, v40
	s_nop 0
	v_mul_f32_e32 v37, v37, v40
	v_mul_f32_e32 v42, v36, v37
	v_mov_b32_e32 v36, v38
	v_mov_b32_e32 v37, v46
	v_pk_mul_f32 v[36:37], v[36:37], v[160:161] op_sel_hi:[1,0]
	v_mov_b32_e32 v46, v39
	v_mul_f32_e32 v38, 0xbfb8aa3b, v37
	v_exp_f32_e32 v38, v38
	v_lshl_add_u64 v[40:41], v[52:53], 0, v[116:117]
	v_add_f32_e32 v38, 1.0, v38
	v_rcp_f32_e32 v38, v38
	s_nop 0
	v_mul_f32_e32 v37, v37, v38
	v_mul_f32_e32 v45, v36, v37
	v_pk_mul_f32 v[36:37], v[50:51], v[160:161] op_sel_hi:[1,0]
	s_nop 0
	v_mul_f32_e32 v38, 0xbfb8aa3b, v37
	v_exp_f32_e32 v38, v38
	s_nop 0
	v_add_f32_e32 v38, 1.0, v38
	v_rcp_f32_e32 v38, v38
	s_nop 0
	v_mul_f32_e32 v37, v37, v38
	v_mul_f32_e32 v38, v36, v37
	v_pk_mul_f32 v[36:37], v[46:47], v[160:161] op_sel_hi:[1,0]
	s_nop 0
	v_mul_f32_e32 v39, 0xbfb8aa3b, v37
	v_exp_f32_e32 v39, v39
	s_nop 0
	v_add_f32_e32 v39, 1.0, v39
	v_rcp_f32_e32 v39, v39
	s_nop 0
	v_mul_f32_e32 v37, v37, v39
	v_mul_f32_e32 v39, v36, v37
	v_cvt_pk_bf16_f32 v36, v56, v48
	v_cvt_pk_bf16_f32 v37, v42, v38
	v_cvt_pk_bf16_f32 v38, v54, v44
	v_cvt_pk_bf16_f32 v39, v45, v39
	global_store_dwordx4 v[40:41], v[36:39], off
	s_nop 1
	v_mov_b32_e32 v38, v24
	v_mov_b32_e32 v39, v32
	v_pk_mul_f32 v[38:39], v[38:39], v[164:165] op_sel_hi:[1,0]
	v_mov_b32_e32 v32, v25
	v_mul_f32_e32 v24, 0xbfb8aa3b, v39
	v_exp_f32_e32 v24, v24
	v_mad_i64_i32 v[36:37], s[4:5], v180, s18, v[134:135]
	v_add_f32_e32 v24, 1.0, v24
	v_rcp_f32_e32 v24, v24
	s_nop 0
	v_mul_f32_e32 v24, v39, v24
	v_mul_f32_e32 v40, v38, v24
	v_mov_b32_e32 v38, v20
	v_mov_b32_e32 v39, v28
	v_pk_mul_f32 v[38:39], v[38:39], v[164:165] op_sel_hi:[1,0]
	v_pk_mul_f32 v[24:25], v[32:33], v[164:165] op_sel_hi:[1,0]
	v_mul_f32_e32 v20, 0xbfb8aa3b, v39
	v_exp_f32_e32 v20, v20
	v_mov_b32_e32 v28, v21
	v_add_f32_e32 v20, 1.0, v20
	v_rcp_f32_e32 v20, v20
	s_nop 0
	v_mul_f32_e32 v20, v39, v20
	v_mul_f32_e32 v38, v38, v20
	v_mul_f32_e32 v20, 0xbfb8aa3b, v25
	v_exp_f32_e32 v20, v20
	s_nop 0
	v_add_f32_e32 v20, 1.0, v20
	v_rcp_f32_e32 v20, v20
	s_nop 0
	v_mul_f32_e32 v20, v25, v20
	v_mul_f32_e32 v32, v24, v20
	v_pk_mul_f32 v[20:21], v[28:29], v[164:165] op_sel_hi:[1,0]
	s_nop 0
	v_mul_f32_e32 v24, 0xbfb8aa3b, v21
	v_exp_f32_e32 v24, v24
	s_nop 0
	v_add_f32_e32 v24, 1.0, v24
	v_rcp_f32_e32 v24, v24
	s_nop 0
	v_mul_f32_e32 v21, v21, v24
	v_mul_f32_e32 v28, v20, v21
	v_mov_b32_e32 v20, v26
	v_mov_b32_e32 v21, v34
	v_pk_mul_f32 v[20:21], v[20:21], v[164:165] op_sel_hi:[1,0]
	v_mov_b32_e32 v34, v27
	v_mul_f32_e32 v24, 0xbfb8aa3b, v21
	v_exp_f32_e32 v24, v24
	s_nop 0
	v_add_f32_e32 v24, 1.0, v24
	v_rcp_f32_e32 v24, v24
	s_nop 0
	v_mul_f32_e32 v21, v21, v24
	v_mul_f32_e32 v26, v20, v21
	v_mov_b32_e32 v20, v22
	v_mov_b32_e32 v21, v30
	v_pk_mul_f32 v[20:21], v[20:21], v[164:165] op_sel_hi:[1,0]
	v_mov_b32_e32 v30, v23
	v_mul_f32_e32 v22, 0xbfb8aa3b, v21
	v_exp_f32_e32 v22, v22
	v_lshl_add_u64 v[24:25], v[36:37], 0, v[116:117]
	v_add_f32_e32 v22, 1.0, v22
	v_rcp_f32_e32 v22, v22
	s_nop 0
	v_mul_f32_e32 v21, v21, v22
	v_mul_f32_e32 v29, v20, v21
	v_pk_mul_f32 v[20:21], v[34:35], v[164:165] op_sel_hi:[1,0]
	s_nop 0
	v_mul_f32_e32 v22, 0xbfb8aa3b, v21
	v_exp_f32_e32 v22, v22
	s_nop 0
	v_add_f32_e32 v22, 1.0, v22
	v_rcp_f32_e32 v22, v22
	s_nop 0
	v_mul_f32_e32 v21, v21, v22
	v_mul_f32_e32 v22, v20, v21
	v_pk_mul_f32 v[20:21], v[30:31], v[164:165] op_sel_hi:[1,0]
	s_nop 0
	v_mul_f32_e32 v23, 0xbfb8aa3b, v21
	v_exp_f32_e32 v23, v23
	s_nop 0
	v_add_f32_e32 v23, 1.0, v23
	v_rcp_f32_e32 v23, v23
	s_nop 0
	v_mul_f32_e32 v21, v21, v23
	v_mul_f32_e32 v23, v20, v21
	v_cvt_pk_bf16_f32 v20, v40, v32
	v_cvt_pk_bf16_f32 v21, v26, v22
	v_cvt_pk_bf16_f32 v22, v38, v28
	v_cvt_pk_bf16_f32 v23, v29, v23
	global_store_dwordx4 v[24:25], v[20:23], off
	s_nop 1
	v_mov_b32_e32 v22, v8
	v_mov_b32_e32 v23, v16
	v_pk_mul_f32 v[22:23], v[22:23], v[132:133] op_sel_hi:[1,0]
	v_mov_b32_e32 v16, v9
	v_mul_f32_e32 v8, 0xbfb8aa3b, v23
	v_exp_f32_e32 v8, v8
	v_mad_i64_i32 v[20:21], s[4:5], v182, s18, v[134:135]
	s_mov_b64 s[4:5], -1
	v_add_f32_e32 v8, 1.0, v8
	v_rcp_f32_e32 v8, v8
	s_nop 0
	v_mul_f32_e32 v8, v23, v8
	v_mul_f32_e32 v24, v22, v8
	v_mov_b32_e32 v22, v4
	v_mov_b32_e32 v23, v12
	v_pk_mul_f32 v[22:23], v[22:23], v[132:133] op_sel_hi:[1,0]
	v_pk_mul_f32 v[8:9], v[16:17], v[132:133] op_sel_hi:[1,0]
	v_mul_f32_e32 v4, 0xbfb8aa3b, v23
	v_exp_f32_e32 v4, v4
	v_mov_b32_e32 v12, v5
	v_add_f32_e32 v4, 1.0, v4
	v_rcp_f32_e32 v4, v4
	s_nop 0
	v_mul_f32_e32 v4, v23, v4
	v_mul_f32_e32 v22, v22, v4
	v_mul_f32_e32 v4, 0xbfb8aa3b, v9
	v_exp_f32_e32 v4, v4
	s_nop 0
	v_add_f32_e32 v4, 1.0, v4
	v_rcp_f32_e32 v4, v4
	s_nop 0
	v_mul_f32_e32 v4, v9, v4
	v_mul_f32_e32 v16, v8, v4
	v_pk_mul_f32 v[4:5], v[12:13], v[132:133] op_sel_hi:[1,0]
	s_nop 0
	v_mul_f32_e32 v8, 0xbfb8aa3b, v5
	v_exp_f32_e32 v8, v8
	s_nop 0
	v_add_f32_e32 v8, 1.0, v8
	v_rcp_f32_e32 v8, v8
	s_nop 0
	v_mul_f32_e32 v5, v5, v8
	v_mul_f32_e32 v12, v4, v5
	v_mov_b32_e32 v4, v10
	v_mov_b32_e32 v5, v18
	v_pk_mul_f32 v[4:5], v[4:5], v[132:133] op_sel_hi:[1,0]
	v_mov_b32_e32 v18, v11
	v_mul_f32_e32 v8, 0xbfb8aa3b, v5
	v_exp_f32_e32 v8, v8
	s_nop 0
	v_add_f32_e32 v8, 1.0, v8
	v_rcp_f32_e32 v8, v8
	s_nop 0
	v_mul_f32_e32 v5, v5, v8
	v_mul_f32_e32 v10, v4, v5
	v_mov_b32_e32 v4, v6
	v_mov_b32_e32 v5, v14
	v_pk_mul_f32 v[4:5], v[4:5], v[132:133] op_sel_hi:[1,0]
	v_mov_b32_e32 v14, v7
	v_mul_f32_e32 v6, 0xbfb8aa3b, v5
	v_exp_f32_e32 v6, v6
	v_lshl_add_u64 v[8:9], v[20:21], 0, v[116:117]
	v_add_f32_e32 v6, 1.0, v6
	v_rcp_f32_e32 v6, v6
	s_nop 0
	v_mul_f32_e32 v5, v5, v6
	v_mul_f32_e32 v13, v4, v5
	v_pk_mul_f32 v[4:5], v[18:19], v[132:133] op_sel_hi:[1,0]
	s_nop 0
	v_mul_f32_e32 v6, 0xbfb8aa3b, v5
	v_exp_f32_e32 v6, v6
	s_nop 0
	v_add_f32_e32 v6, 1.0, v6
	v_rcp_f32_e32 v6, v6
	s_nop 0
	v_mul_f32_e32 v5, v5, v6
	v_mul_f32_e32 v6, v4, v5
	v_pk_mul_f32 v[4:5], v[14:15], v[132:133] op_sel_hi:[1,0]
	s_nop 0
	v_mul_f32_e32 v7, 0xbfb8aa3b, v5
	v_exp_f32_e32 v7, v7
	s_nop 0
	v_add_f32_e32 v7, 1.0, v7
	v_rcp_f32_e32 v7, v7
	s_nop 0
	v_mul_f32_e32 v5, v5, v7
	v_mul_f32_e32 v7, v4, v5
	v_cvt_pk_bf16_f32 v4, v24, v16
	v_cvt_pk_bf16_f32 v5, v10, v6
	v_cvt_pk_bf16_f32 v6, v22, v12
	v_cvt_pk_bf16_f32 v7, v13, v7
	global_store_dwordx4 v[8:9], v[4:7], off
	s_cbranch_vccnz .LBB0_859
	s_andn2_b64 vcc, exec, s[6:7]
	s_cbranch_vccnz .LBB0_858
	s_barrier
	s_branch .LBB0_858
